# speedup vs baseline: 1.0297x; 1.0085x over previous
; __device__ __forceinline__ void finishSM(f32x16& p0, f32x16& p1, float& l_reg, bf16x8& pa0, bf16x8& pa1, bf16x8& pa2, bf16x8& pa3) {
; #pragma unroll
;   for (int r = 0; r < 16; ++r) p0[r] = __builtin_amdgcn_exp2f(p0[r]);
; #pragma unroll
;   for (int r = 0; r < 16; ++r) p1[r] = __builtin_amdgcn_exp2f(p1[r]);
;   float ps = 0;
; #pragma unroll
;   for (int r = 0; r < 16; ++r) ps += p0[r];
; #pragma unroll
;   for (int r = 0; r < 16; ++r) ps += p1[r];
;   { auto rr = __builtin_amdgcn_permlane32_swap(__float_as_uint(ps), __float_as_uint(ps), false, false);
;     ps = __uint_as_float(rr[0]) + __uint_as_float(rr[1]); }
;   l_reg += ps;
;     ...
;   PK4(p0, 0, pa0); PK4(p0, 8, pa1); PK4(p1, 0, pa2); PK4(p1, 8, pa3);
;     ...
; }
; template <int MODE>
; __device__ __forceinline__ void qkt(f32x16& p0, f32x16& p1, const bf16* Ks, const bf16x8* qr, int r32, int hi, float dq, float nsl, int side, float mi) {
;   if (MODE == 0) {
;     if (side != 0) {
;       const float sg = side > 0 ? -nsl : nsl, bb = -sg * dq - mi;
; #pragma unroll
;       for (int r = 0; r < 16; ++r) { const float c = (float)((r & 3) + 8 * (r >> 2)); p0[r] = fmaf(c, sg, bb); p1[r] = fmaf(c + 32.f, sg, bb); }
;     } else {
; #pragma unroll
;       for (int r = 0; r < 16; ++r) { const float c = (float)((r & 3) + 8 * (r >> 2)); p0[r] = fmaf(fabsf(dq - c), nsl, -mi); p1[r] = fmaf(fabsf(dq - (c + 32.f)), nsl, -mi); }
;     }
;   } else {
; #pragma unroll
;     for (int r = 0; r < 16; ++r) { const float c = (float)((r & 3) + 8 * (r >> 2)); p0[r] = (r < 8) ? fmaf(fabsf(dq - c), nsl, -mi) : NEGBIG; p1[r] = NEGBIG; }
;   }
; #pragma unroll
;   for (int d0 = 0; d0 < 8; ++d0) {
;     const int ko = r32 * 256 + ((((d0 & 3) * 32 + hi * 16) ^ ((r32 & 7) << 4))) + (d0 >> 2) * 128;
;     bf16x8 b0 = *reinterpret_cast<const bf16x8*>((const char*)Ks + ko);
;     bf16x8 b1 = *reinterpret_cast<const bf16x8*>((const char*)Ks + ko + 8192);
;     p0 = __builtin_amdgcn_mfma_f32_32x32x16_bf16(b0, qr[d0], p0, 0, 0, 0);
;     p1 = __builtin_amdgcn_mfma_f32_32x32x16_bf16(b1, qr[d0], p1, 0, 0, 0); }
; template <int J> ...
;     ...
;     SBAR(); qkt<0>(pB0, pB1, (bf16*)((char*)K_lds + SHM_K), qr, r32, hi, TILE_DQ(j), nsl, TILE_SIDE(j), mi);
;     finishSM(pA0, pA1, l_reg, pa0, pa1, pa2, pa3); SBAR();
;     SLOAD(SO, j + SDEPTH); SBAR();
;     pv_d0(o, vb0, pa0, pa1, pa2, pa3); SBAR();
;     __syncthreads(); SWAIT(); SWRITE(0, SE);
.LBB0_697:
	v_readfirstlane_b32 s5, v248
	s_add_i32 s92, s6, s3
	s_add_i32 s10, s92, 1
	s_ashr_i32 s11, s10, 31
	s_lshl_b64 s[10:11], s[10:11], 18
	s_add_u32 s10, s89, s10
	s_addc_u32 s11, s24, s11
	s_add_i32 s93, s3, 1
	s_cmp_lt_i32 s93, s30
	s_cselect_b32 s10, s10, s16
	s_cselect_b32 s11, s11, s1
	s_ashr_i32 s93, s92, 31
	s_lshl_b64 s[92:93], s[92:93], 18
	s_add_u32 s92, s0, s92
	s_addc_u32 s93, s25, s93
	ds_read_b128 v[0:3], v230 offset:49152
	ds_read_b128 v[4:7], v230 offset:57344
	v_exp_f32_e32 v74, v74
	v_exp_f32_e32 v75, v75
	v_exp_f32_e32 v76, v76
	s_waitcnt lgkmcnt(1)
	v_mfma_f32_32x32x16_bf16 v[122:137], v[0:3], v[166:169], v[122:137]
	v_exp_f32_e32 v77, v77
	v_exp_f32_e32 v78, v78
	v_exp_f32_e32 v79, v79
	v_exp_f32_e32 v80, v80
	v_exp_f32_e32 v81, v81
	v_exp_f32_e32 v82, v82
	v_exp_f32_e32 v83, v83
	s_waitcnt lgkmcnt(0)
	v_mfma_f32_32x32x16_bf16 v[106:121], v[4:7], v[166:169], v[106:121]
	s_add_i32 m0, s5, 0x8000
	s_nop 0
	global_load_lds_dwordx4 v245, s[10:11]
	ds_read_b128 v[0:3], v231 offset:49152
	ds_read_b128 v[4:7], v231 offset:57344
	v_exp_f32_e32 v84, v84
	v_exp_f32_e32 v85, v85
	v_exp_f32_e32 v86, v86
	v_exp_f32_e32 v87, v87
	v_exp_f32_e32 v88, v88
	v_exp_f32_e32 v89, v89
	s_waitcnt lgkmcnt(1)
	v_mfma_f32_32x32x16_bf16 v[122:137], v[0:3], v[162:165], v[122:137]
	s_add_i32 s4, s3, 1
	s_waitcnt lgkmcnt(0)
	v_mfma_f32_32x32x16_bf16 v[106:121], v[4:7], v[162:165], v[106:121]
	ds_read_b128 v[0:3], v232 offset:49152
	ds_read_b128 v[4:7], v232 offset:57344
	s_waitcnt lgkmcnt(1)
	v_mfma_f32_32x32x16_bf16 v[122:137], v[0:3], v[158:161], v[122:137]
	s_waitcnt lgkmcnt(0)
	v_mfma_f32_32x32x16_bf16 v[106:121], v[4:7], v[158:161], v[106:121]
	s_add_i32 m0, s5, 0x8400
	s_nop 0
	global_load_lds_dwordx4 v246, s[10:11]
	ds_read_b128 v[0:3], v233 offset:49152
	ds_read_b128 v[4:7], v233 offset:57344
	s_waitcnt lgkmcnt(1)
	v_mfma_f32_32x32x16_bf16 v[122:137], v[0:3], v[154:157], v[122:137]
	s_waitcnt lgkmcnt(0)
	v_mfma_f32_32x32x16_bf16 v[106:121], v[4:7], v[154:157], v[106:121]
	ds_read_b128 v[0:3], v230 offset:49280
	ds_read_b128 v[4:7], v230 offset:57472
	s_waitcnt lgkmcnt(1)
	v_mfma_f32_32x32x16_bf16 v[122:137], v[0:3], v[150:153], v[122:137]
	s_waitcnt lgkmcnt(0)
	v_mfma_f32_32x32x16_bf16 v[106:121], v[4:7], v[150:153], v[106:121]
	s_add_i32 m0, s5, 0x4000
	s_nop 0
	global_load_lds_dwordx4 v247, s[92:93]
	ds_read_b128 v[0:3], v231 offset:49280
	ds_read_b128 v[4:7], v231 offset:57472
	s_waitcnt lgkmcnt(1)
	v_mfma_f32_32x32x16_bf16 v[122:137], v[0:3], v[146:149], v[122:137]
	s_waitcnt lgkmcnt(0)
	v_mfma_f32_32x32x16_bf16 v[106:121], v[4:7], v[146:149], v[106:121]
	ds_read_b128 v[0:3], v232 offset:49280
	ds_read_b128 v[4:7], v232 offset:57472
	s_waitcnt lgkmcnt(1)
	v_mfma_f32_32x32x16_bf16 v[122:137], v[0:3], v[142:145], v[122:137]
	s_waitcnt lgkmcnt(0)
	v_mfma_f32_32x32x16_bf16 v[106:121], v[4:7], v[142:145], v[106:121]
	s_add_i32 m0, s5, 0x4380
	s_nop 0
	global_load_lds_dwordx4 v247, s[92:93] offset:128
	ds_read_b128 v[0:3], v233 offset:49280
	ds_read_b128 v[4:7], v233 offset:57472
	s_waitcnt lgkmcnt(1)
	v_mfma_f32_32x32x16_bf16 v[122:137], v[0:3], v[138:141], v[122:137]
	v_exp_f32_e32 v0, v90
	v_exp_f32_e32 v1, v91
	v_exp_f32_e32 v2, v92
	v_exp_f32_e32 v3, v93
	v_exp_f32_e32 v90, v98
	v_add_f32_e32 v98, 0, v0
	v_add_f32_e32 v98, v1, v98
	s_waitcnt lgkmcnt(0)
	v_mfma_f32_32x32x16_bf16 v[106:121], v[4:7], v[138:141], v[106:121]
	v_exp_f32_e32 v4, v94
	v_exp_f32_e32 v5, v95
	v_exp_f32_e32 v6, v96
	v_add_f32_e32 v98, v2, v98
	v_exp_f32_e32 v7, v97
	v_add_f32_e32 v98, v3, v98
	v_add_f32_e32 v98, v4, v98
	v_exp_f32_e32 v91, v99
	v_add_f32_e32 v98, v5, v98
	v_exp_f32_e32 v92, v100
	v_add_f32_e32 v98, v6, v98
	v_exp_f32_e32 v93, v101
	v_add_f32_e32 v98, v7, v98
	v_exp_f32_e32 v94, v102
	v_add_f32_e32 v98, v90, v98
	v_exp_f32_e32 v95, v103
	v_add_f32_e32 v98, v91, v98
	v_exp_f32_e32 v96, v104
	v_add_f32_e32 v98, v92, v98
	v_exp_f32_e32 v97, v105
	v_add_f32_e32 v98, v93, v98
	v_add_f32_e32 v98, v94, v98
	v_add_f32_e32 v98, v95, v98
	v_add_f32_e32 v98, v96, v98
	v_add_f32_e32 v98, v97, v98
	v_add_f32_e32 v98, v74, v98
	v_add_f32_e32 v98, v75, v98
	v_add_f32_e32 v98, v76, v98
	v_add_f32_e32 v98, v77, v98
	v_add_f32_e32 v98, v78, v98
	v_add_f32_e32 v98, v79, v98
	v_add_f32_e32 v98, v80, v98
	v_add_f32_e32 v98, v81, v98
	v_add_f32_e32 v98, v82, v98
	v_add_f32_e32 v98, v83, v98
	v_add_f32_e32 v98, v84, v98
	v_add_f32_e32 v98, v85, v98
	v_add_f32_e32 v98, v86, v98
	v_add_f32_e32 v98, v87, v98
	v_add_f32_e32 v98, v88, v98
	v_add_f32_e32 v234, v89, v98
	v_mov_b32_e32 v235, v234
	v_cvt_pk_bf16_f32 v0, v0, v1
	v_cvt_pk_bf16_f32 v1, v2, v3
	v_cvt_pk_bf16_f32 v2, v4, v5
	v_cvt_pk_bf16_f32 v3, v6, v7
	v_cvt_pk_bf16_f32 v4, v90, v91
	v_cvt_pk_bf16_f32 v5, v92, v93
	v_cvt_pk_bf16_f32 v6, v94, v95
	v_cvt_pk_bf16_f32 v7, v96, v97
	v_cvt_pk_bf16_f32 v74, v74, v75
	v_cvt_pk_bf16_f32 v75, v76, v77
	v_cvt_pk_bf16_f32 v76, v78, v79
	v_cvt_pk_bf16_f32 v77, v80, v81
	v_cvt_pk_bf16_f32 v78, v82, v83
	v_cvt_pk_bf16_f32 v79, v84, v85
	v_cvt_pk_bf16_f32 v80, v86, v87
	v_cvt_pk_bf16_f32 v81, v88, v89
	s_nop 1
	v_permlane32_swap_b32_e32 v234, v235
	v_permlane32_swap_b32_e32 v0, v2
	v_permlane32_swap_b32_e32 v74, v76
	v_permlane32_swap_b32_e32 v75, v77
	v_permlane32_swap_b32_e32 v78, v80
	v_permlane32_swap_b32_e32 v79, v81
	v_permlane32_swap_b32_e32 v1, v3
	v_permlane32_swap_b32_e32 v4, v6
	v_permlane32_swap_b32_e32 v5, v7
	s_add_i32 s9, s6, s3
	s_add_i32 s10, s9, 1
	s_ashr_i32 s11, s10, 31
	s_lshl_b64 s[10:11], s[10:11], 18
	s_add_u32 s92, s89, s10
	s_addc_u32 s93, s24, s11
	s_add_u32 s10, s0, s10
	s_addc_u32 s11, s25, s11
	s_cmp_lt_i32 s4, s30
	s_cselect_b64 vcc, -1, 0
	s_and_b64 s[4:5], vcc, exec
	s_cselect_b32 s5, s93, s1
	s_cselect_b32 s4, s92, s16
	s_cselect_b32 s11, s11, s29
	s_cselect_b32 s10, s10, s28
	s_waitcnt lgkmcnt(0)
; #define PV_WAIT4() do { asm volatile("s_waitcnt lgkmcnt(4)" ::: "memory"); SBAR(); } while (0)
; #define PV_WAIT0() do { asm volatile("s_waitcnt lgkmcnt(0)" ::: "memory"); SBAR(); } while (0)
; #define PV_MM(od, pX, pY, g) do { od = __builtin_amdgcn_mfma_f32_32x32x16_bf16(pX, PK(g.l0, g.h0), od, 0, 0, 0); od = __builtin_amdgcn_mfma_f32_32x32x16_bf16(pY, PK(g.l1, g.h1), od, 0, 0, 0); } while (0)
; template <int MODE>
; __device__ __forceinline__ void qkt(f32x16& p0, f32x16& p1, const bf16* Ks, const bf16x8* qr, int r32, int hi, float dq, float nsl, int side, float mi) {
;   if (MODE == 0) {
;     if (side != 0) {
;       const float sg = side > 0 ? -nsl : nsl, bb = -sg * dq - mi;
; #pragma unroll
;       for (int r = 0; r < 16; ++r) { const float c = (float)((r & 3) + 8 * (r >> 2)); p0[r] = fmaf(c, sg, bb); p1[r] = fmaf(c + 32.f, sg, bb); }
;     } else {
; #pragma unroll
;       for (int r = 0; r < 16; ++r) { const float c = (float)((r & 3) + 8 * (r >> 2)); p0[r] = fmaf(fabsf(dq - c), nsl, -mi); p1[r] = fmaf(fabsf(dq - (c + 32.f)), nsl, -mi); }
;     }
; __device__ __forceinline__ void pv_d0(f32x16* o, int vb, bf16x8 pa0, bf16x8 pa1, bf16x8 pa2, bf16x8 pa3) {
;   asm volatile("s_waitcnt lgkmcnt(0)" ::: "memory");
;   VG a0 = pv_reads<0, 0>(vb), b0 = pv_reads<0, 2>(vb);
;   PV_WAIT4(); PV_MM(o[0], pa0, pa1, a0); VG a1 = pv_reads<1, 0>(vb);
;   PV_WAIT4(); PV_MM(o[0], pa2, pa3, b0); VG b1 = pv_reads<1, 2>(vb);
;   PV_WAIT4(); PV_MM(o[1], pa0, pa1, a1); VG a2 = pv_reads<2, 0>(vb);
;   PV_WAIT4(); PV_MM(o[1], pa2, pa3, b1); VG b2 = pv_reads<2, 2>(vb);
;   PV_WAIT4(); PV_MM(o[2], pa0, pa1, a2); VG a3 = pv_reads<3, 0>(vb);
;   PV_WAIT4(); PV_MM(o[2], pa2, pa3, b2); VG b3 = pv_reads<3, 2>(vb);
;   PV_WAIT4(); PV_MM(o[3], pa0, pa1, a3);
;   PV_WAIT0(); PV_MM(o[3], pa2, pa3, b3);
; }
	ds_read_b64_tr_b16 v[98:99], v220 offset:0
	ds_read_b64_tr_b16 v[100:101], v220 offset:0x800
	ds_read_b64_tr_b16 v[102:103], v220 offset:0x1000
	ds_read_b64_tr_b16 v[104:105], v220 offset:0x1800
	ds_read_b64_tr_b16 v[236:237], v220 offset:0x2000
	ds_read_b64_tr_b16 v[238:239], v220 offset:0x2800
	ds_read_b64_tr_b16 v[240:241], v220 offset:0x3000
	ds_read_b64_tr_b16 v[242:243], v220 offset:0x3800
	s_waitcnt lgkmcnt(4)
	s_nop 0
	v_mfma_f32_32x32x16_bf16 v[58:73], v[0:3], v[98:101], v[58:73]
	ds_read_b64_tr_b16 v[98:99], v220 offset:0x200
	ds_read_b64_tr_b16 v[100:101], v220 offset:0xa00
	v_mfma_f32_32x32x16_bf16 v[58:73], v[4:7], v[102:105], v[58:73]
	ds_read_b64_tr_b16 v[102:103], v220 offset:0x1200
	ds_read_b64_tr_b16 v[104:105], v220 offset:0x1a00
	s_waitcnt lgkmcnt(4)
	v_mfma_f32_32x32x16_bf16 v[58:73], v[74:77], v[236:239], v[58:73]
	ds_read_b64_tr_b16 v[236:237], v220 offset:0x2200
	ds_read_b64_tr_b16 v[238:239], v220 offset:0x2a00
	v_mfma_f32_32x32x16_bf16 v[58:73], v[78:81], v[240:243], v[58:73]
	ds_read_b64_tr_b16 v[240:241], v220 offset:0x3200
	ds_read_b64_tr_b16 v[242:243], v220 offset:0x3a00
	s_waitcnt lgkmcnt(4)
	v_mfma_f32_32x32x16_bf16 v[42:57], v[0:3], v[98:101], v[42:57]
	ds_read_b64_tr_b16 v[98:99], v220 offset:0x400
	ds_read_b64_tr_b16 v[100:101], v220 offset:0xc00
	v_mfma_f32_32x32x16_bf16 v[42:57], v[4:7], v[102:105], v[42:57]
	ds_read_b64_tr_b16 v[102:103], v220 offset:0x1400
	ds_read_b64_tr_b16 v[104:105], v220 offset:0x1c00
	s_waitcnt lgkmcnt(4)
	v_mfma_f32_32x32x16_bf16 v[42:57], v[74:77], v[236:239], v[42:57]
	ds_read_b64_tr_b16 v[236:237], v220 offset:0x2400
	ds_read_b64_tr_b16 v[238:239], v220 offset:0x2c00
	v_mfma_f32_32x32x16_bf16 v[42:57], v[78:81], v[240:243], v[42:57]
	ds_read_b64_tr_b16 v[240:241], v220 offset:0x3400
	ds_read_b64_tr_b16 v[242:243], v220 offset:0x3c00
	s_waitcnt lgkmcnt(4)
	v_mfma_f32_32x32x16_bf16 v[26:41], v[0:3], v[98:101], v[26:41]
	ds_read_b64_tr_b16 v[98:99], v220 offset:0x600
	ds_read_b64_tr_b16 v[100:101], v220 offset:0xe00
	v_mfma_f32_32x32x16_bf16 v[26:41], v[4:7], v[102:105], v[26:41]
	ds_read_b64_tr_b16 v[102:103], v220 offset:0x1600
	ds_read_b64_tr_b16 v[104:105], v220 offset:0x1e00
	s_waitcnt lgkmcnt(4)
	v_mfma_f32_32x32x16_bf16 v[26:41], v[74:77], v[236:239], v[26:41]
	ds_read_b64_tr_b16 v[236:237], v220 offset:0x2600
	ds_read_b64_tr_b16 v[238:239], v220 offset:0x2e00
	v_mfma_f32_32x32x16_bf16 v[26:41], v[78:81], v[240:243], v[26:41]
	ds_read_b64_tr_b16 v[240:241], v220 offset:0x3600
	ds_read_b64_tr_b16 v[242:243], v220 offset:0x3e00
	s_waitcnt lgkmcnt(4)
	v_mfma_f32_32x32x16_bf16 v[10:25], v[0:3], v[98:101], v[10:25]
	s_waitcnt lgkmcnt(0)
	v_mfma_f32_32x32x16_bf16 v[10:25], v[4:7], v[102:105], v[10:25]
	v_mfma_f32_32x32x16_bf16 v[10:25], v[74:77], v[236:239], v[10:25]
	v_mfma_f32_32x32x16_bf16 v[10:25], v[78:81], v[240:243], v[10:25]
	s_cselect_b32 s4, s31, 0x10000000
	s_add_i32 s5, s4, s13
	v_cvt_f32_i32_e32 v0, s91
	s_cmp_lt_i32 s5, 63
	s_cselect_b64 s[10:11], -1, 0
	s_add_i32 s4, s4, s23
	s_cmp_gt_i32 s4, 0
	s_cselect_b64 s[4:5], -1, 0
	v_cndmask_b32_e32 v0, v214, v0, vcc
	s_and_b64 s[4:5], s[10:11], s[4:5]
	v_sub_f32_e32 v0, v176, v0
	s_andn2_b64 vcc, exec, s[4:5]
	s_mov_b64 s[4:5], -1
	s_cbranch_vccz .LBB0_699
	v_cndmask_b32_e64 v2, -v172, v172, s[10:11]
	v_fma_f32 v4, v0, -v2, -v174
	v_fma_f32 v90, 0, v2, v4
	v_add_f32_e32 v91, v2, v4
	v_pk_fma_f32 v[74:75], v[2:3], s[34:35], v[4:5] op_sel_hi:[0,1,0]
	v_pk_fma_f32 v[92:93], v[2:3], s[36:37], v[4:5] op_sel_hi:[0,1,0]
	v_pk_fma_f32 v[76:77], v[2:3], s[38:39], v[4:5] op_sel_hi:[0,1,0]
	v_pk_fma_f32 v[94:95], v[2:3], s[40:41], v[4:5] op_sel_hi:[0,1,0]
	v_pk_fma_f32 v[78:79], v[2:3], s[42:43], v[4:5] op_sel_hi:[0,1,0]
	v_pk_fma_f32 v[96:97], v[2:3], s[44:45], v[4:5] op_sel_hi:[0,1,0]
	v_pk_fma_f32 v[80:81], v[2:3], s[46:47], v[4:5] op_sel_hi:[0,1,0]
	v_pk_fma_f32 v[98:99], v[2:3], s[48:49], v[4:5] op_sel_hi:[0,1,0]
	v_pk_fma_f32 v[82:83], v[2:3], s[50:51], v[4:5] op_sel_hi:[0,1,0]
	v_pk_fma_f32 v[100:101], v[2:3], s[52:53], v[4:5] op_sel_hi:[0,1,0]
	v_pk_fma_f32 v[84:85], v[2:3], s[54:55], v[4:5] op_sel_hi:[0,1,0]
	v_pk_fma_f32 v[102:103], v[2:3], s[56:57], v[4:5] op_sel_hi:[0,1,0]
	v_pk_fma_f32 v[86:87], v[2:3], s[58:59], v[4:5] op_sel_hi:[0,1,0]
	v_fmamk_f32 v88, v2, 0x42680000, v4
	v_pk_fma_f32 v[104:105], v[2:3], s[60:61], v[4:5] op_sel_hi:[0,1,0]
	v_fmac_f32_e32 v4, 0x426c0000, v2
	s_mov_b64 s[4:5], 0
	v_mov_b32_e32 v89, v4

; __device__ __forceinline__ void finishSM(f32x16& p0, f32x16& p1, float& l_reg, bf16x8& pa0, bf16x8& pa1, bf16x8& pa2, bf16x8& pa3) {
; #pragma unroll
;   for (int r = 0; r < 16; ++r) p0[r] = __builtin_amdgcn_exp2f(p0[r]);
; #pragma unroll
;   for (int r = 0; r < 16; ++r) p1[r] = __builtin_amdgcn_exp2f(p1[r]);
;   float ps = 0;
; #pragma unroll
;   for (int r = 0; r < 16; ++r) ps += p0[r];
; #pragma unroll
;   for (int r = 0; r < 16; ++r) ps += p1[r];
;   { auto rr = __builtin_amdgcn_permlane32_swap(__float_as_uint(ps), __float_as_uint(ps), false, false);
;     ps = __uint_as_float(rr[0]) + __uint_as_float(rr[1]); }
;   l_reg += ps;
;     ...
;   PK4(p0, 0, pa0); PK4(p0, 8, pa1); PK4(p1, 0, pa2); PK4(p1, 8, pa3);
;     ...
; }
; template <int MODE>
; __device__ __forceinline__ void qkt(f32x16& p0, f32x16& p1, const bf16* Ks, const bf16x8* qr, int r32, int hi, float dq, float nsl, int side, float mi) {
;   if (MODE == 0) {
;     if (side != 0) {
;       const float sg = side > 0 ? -nsl : nsl, bb = -sg * dq - mi;
; #pragma unroll
;       for (int r = 0; r < 16; ++r) { const float c = (float)((r & 3) + 8 * (r >> 2)); p0[r] = fmaf(c, sg, bb); p1[r] = fmaf(c + 32.f, sg, bb); }
;     } else {
; #pragma unroll
;       for (int r = 0; r < 16; ++r) { const float c = (float)((r & 3) + 8 * (r >> 2)); p0[r] = fmaf(fabsf(dq - c), nsl, -mi); p1[r] = fmaf(fabsf(dq - (c + 32.f)), nsl, -mi); }
;     }
;   } else {
; #pragma unroll
;     for (int r = 0; r < 16; ++r) { const float c = (float)((r & 3) + 8 * (r >> 2)); p0[r] = (r < 8) ? fmaf(fabsf(dq - c), nsl, -mi) : NEGBIG; p1[r] = NEGBIG; }
;   }
; #pragma unroll
;   for (int d0 = 0; d0 < 8; ++d0) {
;     const int ko = r32 * 256 + ((((d0 & 3) * 32 + hi * 16) ^ ((r32 & 7) << 4))) + (d0 >> 2) * 128;
;     bf16x8 b0 = *reinterpret_cast<const bf16x8*>((const char*)Ks + ko);
;     bf16x8 b1 = *reinterpret_cast<const bf16x8*>((const char*)Ks + ko + 8192);
;     p0 = __builtin_amdgcn_mfma_f32_32x32x16_bf16(b0, qr[d0], p0, 0, 0, 0);
;     p1 = __builtin_amdgcn_mfma_f32_32x32x16_bf16(b1, qr[d0], p1, 0, 0, 0); }
; template <int J> ...
;     ...
;     SBAR(); qkt<0>(pA0, pA1, K_lds, qr, r32, hi, TILE_DQ(j + 1), nsl, TILE_SIDE(j + 1), mi);
;     finishSM(pB0, pB1, l_reg, pa0, pa1, pa2, pa3); SBAR();
;     if (SDEPTH == 1 || j + 3 < NT) SLOAD(SE, j + 1 + SDEPTH); SBAR();
;     pv_d0(o, vb0 + (int)SHM_V, pa0, pa1, pa2, pa3); SBAR();
.LBB0_701:
	s_waitcnt vmcnt(0)
	s_barrier
	v_readfirstlane_b32 s5, v248
	s_add_i32 s92, s6, s3
	s_add_i32 s10, s92, 2
	s_ashr_i32 s11, s10, 31
	s_lshl_b64 s[10:11], s[10:11], 18
	s_add_u32 s10, s89, s10
	s_addc_u32 s11, s24, s11
	s_add_i32 s93, s3, 2
	s_cmp_lt_i32 s93, s30
	s_cselect_b32 s10, s10, s16
	s_cselect_b32 s11, s11, s1
	s_add_i32 s92, s92, 1
	s_ashr_i32 s93, s92, 31
	s_lshl_b64 s[92:93], s[92:93], 18
	s_add_u32 s92, s0, s92
	s_addc_u32 s93, s25, s93
	v_add_f32_e32 v0, v234, v235
	v_add_f32_e32 v173, v227, v0
	ds_read_b128 v[0:3], v230 offset:32768
	ds_read_b128 v[4:7], v230 offset:40960
	v_exp_f32_e32 v106, v106
	v_exp_f32_e32 v107, v107
	s_waitcnt lgkmcnt(1)
	v_mfma_f32_32x32x16_bf16 v[90:105], v[0:3], v[166:169], v[90:105]
	v_exp_f32_e32 v108, v108
	v_exp_f32_e32 v109, v109
	v_exp_f32_e32 v110, v110
	v_exp_f32_e32 v111, v111
	v_exp_f32_e32 v112, v112
	v_exp_f32_e32 v113, v113
	v_exp_f32_e32 v114, v114
	s_waitcnt lgkmcnt(0)
	v_mfma_f32_32x32x16_bf16 v[74:89], v[4:7], v[166:169], v[74:89]
	s_add_i32 m0, s5, 0xc000
	s_nop 0
	global_load_lds_dwordx4 v245, s[10:11]
	ds_read_b128 v[0:3], v231 offset:32768
	ds_read_b128 v[4:7], v231 offset:40960
	v_exp_f32_e32 v115, v115
	v_exp_f32_e32 v116, v116
	v_exp_f32_e32 v117, v117
	v_exp_f32_e32 v118, v118
	v_exp_f32_e32 v119, v119
	v_exp_f32_e32 v120, v120
	s_waitcnt lgkmcnt(1)
	v_mfma_f32_32x32x16_bf16 v[90:105], v[0:3], v[162:165], v[90:105]
	v_exp_f32_e32 v121, v121
	s_waitcnt lgkmcnt(0)
	v_mfma_f32_32x32x16_bf16 v[74:89], v[4:7], v[162:165], v[74:89]
	ds_read_b128 v[0:3], v232 offset:32768
	ds_read_b128 v[4:7], v232 offset:40960
	s_waitcnt lgkmcnt(1)
	v_mfma_f32_32x32x16_bf16 v[90:105], v[0:3], v[158:161], v[90:105]
	s_waitcnt lgkmcnt(0)
	v_mfma_f32_32x32x16_bf16 v[74:89], v[4:7], v[158:161], v[74:89]
	s_add_i32 m0, s5, 0xc400
	s_nop 0
	global_load_lds_dwordx4 v246, s[10:11]
	ds_read_b128 v[0:3], v233 offset:32768
	ds_read_b128 v[4:7], v233 offset:40960
	s_waitcnt lgkmcnt(1)
	v_mfma_f32_32x32x16_bf16 v[90:105], v[0:3], v[154:157], v[90:105]
	s_waitcnt lgkmcnt(0)
	v_mfma_f32_32x32x16_bf16 v[74:89], v[4:7], v[154:157], v[74:89]
	ds_read_b128 v[0:3], v230 offset:32896
	ds_read_b128 v[4:7], v230 offset:41088
	s_waitcnt lgkmcnt(1)
	v_mfma_f32_32x32x16_bf16 v[90:105], v[0:3], v[150:153], v[90:105]
	s_waitcnt lgkmcnt(0)
	v_mfma_f32_32x32x16_bf16 v[74:89], v[4:7], v[150:153], v[74:89]
	s_add_i32 m0, s5, 0x0
	s_nop 0
	global_load_lds_dwordx4 v247, s[92:93]
	ds_read_b128 v[0:3], v231 offset:32896
	ds_read_b128 v[4:7], v231 offset:41088
	s_waitcnt lgkmcnt(1)
	v_mfma_f32_32x32x16_bf16 v[90:105], v[0:3], v[146:149], v[90:105]
	s_waitcnt lgkmcnt(0)
	v_mfma_f32_32x32x16_bf16 v[74:89], v[4:7], v[146:149], v[74:89]
	ds_read_b128 v[0:3], v232 offset:32896
	ds_read_b128 v[4:7], v232 offset:41088
	s_waitcnt lgkmcnt(1)
	v_mfma_f32_32x32x16_bf16 v[90:105], v[0:3], v[142:145], v[90:105]
	s_waitcnt lgkmcnt(0)
	v_mfma_f32_32x32x16_bf16 v[74:89], v[4:7], v[142:145], v[74:89]
	s_add_i32 m0, s5, 0x380
	s_nop 0
	global_load_lds_dwordx4 v247, s[92:93] offset:128
	ds_read_b128 v[0:3], v233 offset:32896
	ds_read_b128 v[4:7], v233 offset:41088
	s_waitcnt lgkmcnt(1)
	v_mfma_f32_32x32x16_bf16 v[90:105], v[0:3], v[138:141], v[90:105]
	v_exp_f32_e32 v0, v122
	v_exp_f32_e32 v1, v123
	v_exp_f32_e32 v2, v124
	v_exp_f32_e32 v3, v125
	v_exp_f32_e32 v122, v130
	v_add_f32_e32 v130, 0, v0
	v_add_f32_e32 v130, v1, v130
	s_waitcnt lgkmcnt(0)
	v_mfma_f32_32x32x16_bf16 v[74:89], v[4:7], v[138:141], v[74:89]
	v_exp_f32_e32 v4, v126
	v_exp_f32_e32 v5, v127
	v_exp_f32_e32 v6, v128
	v_add_f32_e32 v130, v2, v130
	v_exp_f32_e32 v7, v129
	v_add_f32_e32 v130, v3, v130
	v_add_f32_e32 v130, v4, v130
	v_exp_f32_e32 v123, v131
	v_add_f32_e32 v130, v5, v130
	v_exp_f32_e32 v124, v132
	v_add_f32_e32 v130, v6, v130
	v_exp_f32_e32 v125, v133
	v_add_f32_e32 v130, v7, v130
	v_exp_f32_e32 v126, v134
	v_add_f32_e32 v130, v122, v130
	v_exp_f32_e32 v127, v135
	v_add_f32_e32 v130, v123, v130
	v_exp_f32_e32 v128, v136
	v_add_f32_e32 v130, v124, v130
	v_exp_f32_e32 v129, v137
	v_add_f32_e32 v130, v125, v130
	v_add_f32_e32 v130, v126, v130
	v_add_f32_e32 v130, v127, v130
	v_add_f32_e32 v130, v128, v130
	v_add_f32_e32 v130, v129, v130
	v_add_f32_e32 v130, v106, v130
	v_add_f32_e32 v130, v107, v130
	v_add_f32_e32 v130, v108, v130
	v_add_f32_e32 v130, v109, v130
	v_add_f32_e32 v130, v110, v130
	v_add_f32_e32 v130, v111, v130
	v_add_f32_e32 v130, v112, v130
	v_add_f32_e32 v130, v113, v130
	v_add_f32_e32 v130, v114, v130
	v_add_f32_e32 v130, v115, v130
	v_add_f32_e32 v130, v116, v130
	v_add_f32_e32 v130, v117, v130
	v_add_f32_e32 v130, v118, v130
	v_add_f32_e32 v130, v119, v130
	v_add_f32_e32 v130, v120, v130
	v_add_f32_e32 v130, v121, v130
	v_mov_b32_e32 v131, v130
	s_nop 1
	v_permlane32_swap_b32_e32 v130, v131
	v_add_f32_e32 v130, v130, v131
	v_add_f32_e32 v227, v173, v130
	v_cvt_pk_bf16_f32 v0, v0, v1
	v_cvt_pk_bf16_f32 v1, v2, v3
	v_cvt_pk_bf16_f32 v2, v4, v5
	v_cvt_pk_bf16_f32 v3, v6, v7
	v_cvt_pk_bf16_f32 v4, v122, v123
	v_cvt_pk_bf16_f32 v5, v124, v125
	v_cvt_pk_bf16_f32 v6, v126, v127
	v_cvt_pk_bf16_f32 v7, v128, v129
	v_cvt_pk_bf16_f32 v106, v106, v107
	v_cvt_pk_bf16_f32 v107, v108, v109
	v_cvt_pk_bf16_f32 v108, v110, v111
	v_cvt_pk_bf16_f32 v109, v112, v113
	v_cvt_pk_bf16_f32 v110, v114, v115
	v_cvt_pk_bf16_f32 v111, v116, v117
	v_cvt_pk_bf16_f32 v112, v118, v119
	v_cvt_pk_bf16_f32 v113, v120, v121
	s_nop 0
	v_permlane32_swap_b32_e32 v0, v2
	v_permlane32_swap_b32_e32 v1, v3
	v_permlane32_swap_b32_e32 v4, v6
	v_permlane32_swap_b32_e32 v5, v7
	v_permlane32_swap_b32_e32 v106, v108
	v_permlane32_swap_b32_e32 v107, v109
	v_permlane32_swap_b32_e32 v110, v112
	v_permlane32_swap_b32_e32 v111, v113
	s_add_i32 s10, s9, 2
	s_ashr_i32 s11, s10, 31
	s_add_i32 s4, s3, 2
	s_lshl_b64 s[10:11], s[10:11], 18
	s_add_u32 s5, s89, s10
	s_addc_u32 s9, s24, s11
	s_add_u32 s92, s0, s10
	s_addc_u32 s93, s25, s11
	s_cmp_lt_i32 s4, s30
	s_cselect_b32 s11, s9, s1
	s_cselect_b32 s10, s5, s16
	s_cselect_b32 s93, s93, s29
	s_cselect_b32 s92, s92, s28
	s_waitcnt lgkmcnt(0)
; #define SBAR() __builtin_amdgcn_sched_barrier(0)
; #define SWRITE(b, i) do { *(bf16x8*)((char*)V_lds + (b) * SHM_V + vst0) = sr_[i].vs0;          \
;     *(bf16x8*)((char*)V_lds + (b) * SHM_V + vst1) = sr_[i].vs1; int kc = sc * 2;               \
;     *(bf16x8*)((char*)K_lds + (b) * SHM_K + KSWZ(sr, kc)) = sr_[i].ks0;                       \
;     *(bf16x8*)((char*)K_lds + (b) * SHM_K + KSWZ(32 + sr, kc)) = sr_[i].ks1; } while (0)
; #define SWAIT() do { if constexpr (SDEPTH == 2) asm volatile("s_waitcnt vmcnt(4)" ::: "memory"); else asm volatile("s_waitcnt vmcnt(0)" ::: "memory"); } while (0)
; template <int MODE>
; __device__ __forceinline__ void qkt(f32x16& p0, f32x16& p1, const bf16* Ks, const bf16x8* qr, int r32, int hi, float dq, float nsl, int side, float mi) {
;   if (MODE == 0) {
;     if (side != 0) {
;       const float sg = side > 0 ? -nsl : nsl, bb = -sg * dq - mi;
; #pragma unroll
;       for (int r = 0; r < 16; ++r) { const float c = (float)((r & 3) + 8 * (r >> 2)); p0[r] = fmaf(c, sg, bb); p1[r] = fmaf(c + 32.f, sg, bb); }
;     } else {
; #pragma unroll
;       for (int r = 0; r < 16; ++r) { const float c = (float)((r & 3) + 8 * (r >> 2)); p0[r] = fmaf(fabsf(dq - c), nsl, -mi); p1[r] = fmaf(fabsf(dq - (c + 32.f)), nsl, -mi); }
;     }
; template <int J> ...
;     ...
;     pv_d0(o, vb0 + (int)SHM_V, pa0, pa1, pa2, pa3); SBAR();
;     __syncthreads(); SWAIT(); SWRITE(1, SO);
;     __syncthreads();
;   }
	ds_read_b64_tr_b16 v[130:131], v229 offset:0
	ds_read_b64_tr_b16 v[132:133], v229 offset:0x800
	ds_read_b64_tr_b16 v[134:135], v229 offset:0x1000
	ds_read_b64_tr_b16 v[136:137], v229 offset:0x1800
	ds_read_b64_tr_b16 v[234:235], v229 offset:0x2000
	ds_read_b64_tr_b16 v[236:237], v229 offset:0x2800
	ds_read_b64_tr_b16 v[238:239], v229 offset:0x3000
	ds_read_b64_tr_b16 v[240:241], v229 offset:0x3800
	s_waitcnt lgkmcnt(4)
	s_nop 0
	v_mfma_f32_32x32x16_bf16 v[58:73], v[0:3], v[130:133], v[58:73]
	ds_read_b64_tr_b16 v[130:131], v229 offset:0x200
	ds_read_b64_tr_b16 v[132:133], v229 offset:0xa00
	v_mfma_f32_32x32x16_bf16 v[58:73], v[4:7], v[134:137], v[58:73]
	ds_read_b64_tr_b16 v[134:135], v229 offset:0x1200
	ds_read_b64_tr_b16 v[136:137], v229 offset:0x1a00
	s_waitcnt lgkmcnt(4)
	v_mfma_f32_32x32x16_bf16 v[58:73], v[106:109], v[234:237], v[58:73]
	ds_read_b64_tr_b16 v[234:235], v229 offset:0x2200
	ds_read_b64_tr_b16 v[236:237], v229 offset:0x2a00
	v_mfma_f32_32x32x16_bf16 v[58:73], v[110:113], v[238:241], v[58:73]
	ds_read_b64_tr_b16 v[238:239], v229 offset:0x3200
	ds_read_b64_tr_b16 v[240:241], v229 offset:0x3a00
	s_waitcnt lgkmcnt(4)
	v_mfma_f32_32x32x16_bf16 v[42:57], v[0:3], v[130:133], v[42:57]
	ds_read_b64_tr_b16 v[130:131], v229 offset:0x400
	ds_read_b64_tr_b16 v[132:133], v229 offset:0xc00
	v_mfma_f32_32x32x16_bf16 v[42:57], v[4:7], v[134:137], v[42:57]
	ds_read_b64_tr_b16 v[134:135], v229 offset:0x1400
	ds_read_b64_tr_b16 v[136:137], v229 offset:0x1c00
	s_waitcnt lgkmcnt(4)
	v_mfma_f32_32x32x16_bf16 v[42:57], v[106:109], v[234:237], v[42:57]
	ds_read_b64_tr_b16 v[234:235], v229 offset:0x2400
	ds_read_b64_tr_b16 v[236:237], v229 offset:0x2c00
	v_mfma_f32_32x32x16_bf16 v[42:57], v[110:113], v[238:241], v[42:57]
	ds_read_b64_tr_b16 v[238:239], v229 offset:0x3400
	ds_read_b64_tr_b16 v[240:241], v229 offset:0x3c00
	s_waitcnt lgkmcnt(4)
	v_mfma_f32_32x32x16_bf16 v[26:41], v[0:3], v[130:133], v[26:41]
	ds_read_b64_tr_b16 v[130:131], v229 offset:0x600
	ds_read_b64_tr_b16 v[132:133], v229 offset:0xe00
	v_mfma_f32_32x32x16_bf16 v[26:41], v[4:7], v[134:137], v[26:41]
	ds_read_b64_tr_b16 v[134:135], v229 offset:0x1600
	ds_read_b64_tr_b16 v[136:137], v229 offset:0x1e00
	s_waitcnt lgkmcnt(4)
	v_mfma_f32_32x32x16_bf16 v[26:41], v[106:109], v[234:237], v[26:41]
	ds_read_b64_tr_b16 v[234:235], v229 offset:0x2600
	ds_read_b64_tr_b16 v[236:237], v229 offset:0x2e00
	v_mfma_f32_32x32x16_bf16 v[26:41], v[110:113], v[238:241], v[26:41]
	ds_read_b64_tr_b16 v[238:239], v229 offset:0x3600
	ds_read_b64_tr_b16 v[240:241], v229 offset:0x3e00
	s_waitcnt lgkmcnt(4)
	v_mfma_f32_32x32x16_bf16 v[10:25], v[0:3], v[130:133], v[10:25]
	s_waitcnt lgkmcnt(0)
	v_mfma_f32_32x32x16_bf16 v[10:25], v[4:7], v[134:137], v[10:25]
	v_mfma_f32_32x32x16_bf16 v[10:25], v[106:109], v[234:237], v[10:25]
	v_mfma_f32_32x32x16_bf16 v[10:25], v[110:113], v[238:241], v[10:25]
	s_addk_i32 s31, 0xff80
	s_addk_i32 s91, 0x80
	s_add_i32 s3, s3, 3
	s_cmp_ge_i32 s3, s7
	s_cbranch_scc1 .Lmy_i1_exit0
	s_mov_b32 s3, s4
	s_sub_i32 s4, s91, 64
	s_add_i32 s9, s31, 64
	s_cmp_lt_i32 s3, s30
	s_cselect_b64 vcc, -1, 0
	v_cvt_f32_i32_e32 v0, s4
	s_and_b64 s[4:5], vcc, exec
	s_cselect_b32 s4, s9, 0x10000000
	s_add_i32 s5, s4, s13
	s_cmp_lt_i32 s5, 63
	s_cselect_b64 s[10:11], -1, 0
	s_add_i32 s4, s4, s23
	s_cmp_gt_i32 s4, 0
	s_cselect_b64 s[4:5], -1, 0
	v_cndmask_b32_e32 v0, v214, v0, vcc
	s_and_b64 s[4:5], s[10:11], s[4:5]
	v_sub_f32_e32 v0, v176, v0
	s_andn2_b64 vcc, exec, s[4:5]
	s_mov_b64 s[4:5], -1
	s_cbranch_vccz .Lmy_i1_ha
	v_cndmask_b32_e64 v2, -v172, v172, s[10:11]
	v_fma_f32 v4, v0, -v2, -v174
	v_fma_f32 v122, 0, v2, v4
	v_add_f32_e32 v123, v2, v4
	v_pk_fma_f32 v[106:107], v[2:3], s[34:35], v[4:5] op_sel_hi:[0,1,0]
	v_pk_fma_f32 v[124:125], v[2:3], s[36:37], v[4:5] op_sel_hi:[0,1,0]
	v_pk_fma_f32 v[108:109], v[2:3], s[38:39], v[4:5] op_sel_hi:[0,1,0]
	v_pk_fma_f32 v[126:127], v[2:3], s[40:41], v[4:5] op_sel_hi:[0,1,0]
	v_pk_fma_f32 v[110:111], v[2:3], s[42:43], v[4:5] op_sel_hi:[0,1,0]
	v_pk_fma_f32 v[128:129], v[2:3], s[44:45], v[4:5] op_sel_hi:[0,1,0]
	v_pk_fma_f32 v[112:113], v[2:3], s[46:47], v[4:5] op_sel_hi:[0,1,0]
	v_pk_fma_f32 v[130:131], v[2:3], s[48:49], v[4:5] op_sel_hi:[0,1,0]
	v_pk_fma_f32 v[114:115], v[2:3], s[50:51], v[4:5] op_sel_hi:[0,1,0]
	v_pk_fma_f32 v[132:133], v[2:3], s[52:53], v[4:5] op_sel_hi:[0,1,0]
	v_pk_fma_f32 v[116:117], v[2:3], s[54:55], v[4:5] op_sel_hi:[0,1,0]
	v_pk_fma_f32 v[134:135], v[2:3], s[56:57], v[4:5] op_sel_hi:[0,1,0]
	v_pk_fma_f32 v[118:119], v[2:3], s[58:59], v[4:5] op_sel_hi:[0,1,0]
	v_fmamk_f32 v120, v2, 0x42680000, v4
	v_pk_fma_f32 v[136:137], v[2:3], s[60:61], v[4:5] op_sel_hi:[0,1,0]
	v_fmac_f32_e32 v4, 0x426c0000, v2
	s_mov_b64 s[4:5], 0
	v_mov_b32_e32 v121, v4

; #define SBAR() __builtin_amdgcn_sched_barrier(0)
; #define TILE_DQ(ti) (qposf - (float)TILE_KPOS(ti))
; #define TILE_SIDE(ti) (qlo - TILE_KPOS(ti) >= 63 ? 1 : (qhi - TILE_KPOS(ti) <= 0 ? -1 : 0))
; #define SLOAD(i, ti) do { const bf16* kp_ = TILE_K(ti); const bf16* vp_ = TILE_V(ti); \
;     sr_[i].vs0 = *(const ATT_GAS bf16x8*)(&vp_[(long)sr * LD + sc]); sr_[i].vs1 = *(const ATT_GAS bf16x8*)(&vp_[(long)(32 + sr) * LD + sc]); \
;     sr_[i].ks0 = *(const ATT_GAS bf16x8*)(&kp_[(long)sr * LD + sc]); sr_[i].ks1 = *(const ATT_GAS bf16x8*)(&kp_[(long)(32 + sr) * LD + sc]); } while (0)
; #define SWRITE(b, i) do { *(bf16x8*)((char*)V_lds + (b) * SHM_V + vst0) = sr_[i].vs0;          \
;     *(bf16x8*)((char*)V_lds + (b) * SHM_V + vst1) = sr_[i].vs1; int kc = sc * 2;               \
;     *(bf16x8*)((char*)K_lds + (b) * SHM_K + KSWZ(sr, kc)) = sr_[i].ks0;                       \
;     *(bf16x8*)((char*)K_lds + (b) * SHM_K + KSWZ(32 + sr, kc)) = sr_[i].ks1; } while (0)
; #define SWAIT() do { if constexpr (SDEPTH == 2) asm volatile("s_waitcnt vmcnt(4)" ::: "memory"); else asm volatile("s_waitcnt vmcnt(0)" ::: "memory"); } while (0)
; template <int J> ...
;     ...
;     __syncthreads(); SWAIT(); SWRITE(0, SE);
;     __syncthreads();
;     SBAR(); qkt<0>(pA0, pA1, K_lds, qr, r32, hi, TILE_DQ(j + 1), nsl, TILE_SIDE(j + 1), mi);
;     finishSM(pB0, pB1, l_reg, pa0, pa1, pa2, pa3); SBAR();
;     if (SDEPTH == 1 || j + 3 < NT) SLOAD(SE, j + 1 + SDEPTH); SBAR();
;     pv_d0(o, vb0 + (int)SHM_V, pa0, pa1, pa2, pa3); SBAR();
;     __syncthreads(); SWAIT(); SWRITE(1, SO);
;     __syncthreads();
;   }
;   SBAR(); qkt<0>(pB0, pB1, (bf16*)((char*)K_lds + SHM_K), qr, r32, hi, TILE_DQ(NT - 1), nsl, TILE_SIDE(NT - 1), mi);
.Lmy_i1_hb:
	s_waitcnt vmcnt(0)
	s_barrier
	s_branch .LBB0_697
.Lmy_i1_exit0:
	s_waitcnt vmcnt(0)
	s_barrier
.Lmy_i1_exit:
	v_readfirstlane_b32 s92, v248
	s_add_i32 s4, s6, s7
	s_add_i32 s4, s4, -1
	s_ashr_i32 s5, s4, 31
	s_lshl_b64 s[4:5], s[4:5], 18
	s_add_u32 s4, s0, s4
	s_addc_u32 s5, s25, s5
	s_cmp_gt_i32 s7, s30
	s_cselect_b32 s4, s28, s4
	s_cselect_b32 s5, s29, s5
	s_add_i32 m0, s92, 0x4000
	s_nop 0
	global_load_lds_dwordx4 v247, s[4:5]
	s_add_i32 m0, s92, 0x4380
	s_nop 0
	global_load_lds_dwordx4 v247, s[4:5] offset:128
	s_branch .LBB0_704

; #define SBAR() __builtin_amdgcn_sched_barrier(0)
; __device__ __forceinline__ void finishSM(f32x16& p0, f32x16& p1, float& l_reg, bf16x8& pa0, bf16x8& pa1, bf16x8& pa2, bf16x8& pa3) {
; #pragma unroll
;   for (int r = 0; r < 16; ++r) p0[r] = __builtin_amdgcn_exp2f(p0[r]);
; #pragma unroll
;   for (int r = 0; r < 16; ++r) p1[r] = __builtin_amdgcn_exp2f(p1[r]);
;   float ps = 0;
; #pragma unroll
;   for (int r = 0; r < 16; ++r) ps += p0[r];
; #pragma unroll
;   for (int r = 0; r < 16; ++r) ps += p1[r];
;   { auto rr = __builtin_amdgcn_permlane32_swap(__float_as_uint(ps), __float_as_uint(ps), false, false);
;     ps = __uint_as_float(rr[0]) + __uint_as_float(rr[1]); }
;   l_reg += ps;
;     ...
;   PK4(p0, 0, pa0); PK4(p0, 8, pa1); PK4(p1, 0, pa2); PK4(p1, 8, pa3);
;     ...
; }
; template <int MODE>
; __device__ __forceinline__ void qkt(f32x16& p0, f32x16& p1, const bf16* Ks, const bf16x8* qr, int r32, int hi, float dq, float nsl, int side, float mi) {
;   if (MODE == 0) {
;     if (side != 0) {
;       const float sg = side > 0 ? -nsl : nsl, bb = -sg * dq - mi;
; #pragma unroll
;       for (int r = 0; r < 16; ++r) { const float c = (float)((r & 3) + 8 * (r >> 2)); p0[r] = fmaf(c, sg, bb); p1[r] = fmaf(c + 32.f, sg, bb); }
;     } else {
; #pragma unroll
;       for (int r = 0; r < 16; ++r) { const float c = (float)((r & 3) + 8 * (r >> 2)); p0[r] = fmaf(fabsf(dq - c), nsl, -mi); p1[r] = fmaf(fabsf(dq - (c + 32.f)), nsl, -mi); }
;     }
;   } else {
; #pragma unroll
;     for (int r = 0; r < 16; ++r) { const float c = (float)((r & 3) + 8 * (r >> 2)); p0[r] = (r < 8) ? fmaf(fabsf(dq - c), nsl, -mi) : NEGBIG; p1[r] = NEGBIG; }
;   }
; #pragma unroll
;   for (int d0 = 0; d0 < 8; ++d0) {
;     const int ko = r32 * 256 + ((((d0 & 3) * 32 + hi * 16) ^ ((r32 & 7) << 4))) + (d0 >> 2) * 128;
;     bf16x8 b0 = *reinterpret_cast<const bf16x8*>((const char*)Ks + ko);
;     bf16x8 b1 = *reinterpret_cast<const bf16x8*>((const char*)Ks + ko + 8192);
;     p0 = __builtin_amdgcn_mfma_f32_32x32x16_bf16(b0, qr[d0], p0, 0, 0, 0);
;     p1 = __builtin_amdgcn_mfma_f32_32x32x16_bf16(b1, qr[d0], p1, 0, 0, 0); }
; template <int J> ...
;     ...
;   SBAR(); qkt<0>(pB0, pB1, (bf16*)((char*)K_lds + SHM_K), qr, r32, hi, TILE_DQ(NT - 1), nsl, TILE_SIDE(NT - 1), mi);
;   finishSM(pA0, pA1, l_reg, pa0, pa1, pa2, pa3); SBAR();
;   pv_d0(o, vb0, pa0, pa1, pa2, pa3); SBAR();
.LBB0_708:
	s_movk_i32 s4, 0x70
	v_bitop3_b32 v0, v170, v222, s4 bitop3:0x78
	v_add3_u32 v173, 0, v0, v228
	ds_read_b128 v[0:3], v173 offset:49152
	ds_read_b128 v[4:7], v173 offset:57344
	s_movk_i32 s4, 0x60
	v_exp_f32_e32 v81, v81
	v_exp_f32_e32 v82, v82
	s_waitcnt lgkmcnt(1)
	v_mfma_f32_32x32x16_bf16 v[122:137], v[0:3], v[166:169], v[122:137]
	v_bitop3_b32 v0, v170, v221, 32 bitop3:0x36
	v_exp_f32_e32 v83, v83
	v_exp_f32_e32 v84, v84
	v_exp_f32_e32 v85, v85
	v_exp_f32_e32 v86, v86
	v_exp_f32_e32 v87, v87
	v_exp_f32_e32 v88, v88
	s_waitcnt lgkmcnt(0)
	v_mfma_f32_32x32x16_bf16 v[106:121], v[4:7], v[166:169], v[106:121]
	v_add3_u32 v166, 0, v0, v228
	ds_read_b128 v[0:3], v166 offset:49152
	ds_read_b128 v[4:7], v166 offset:57344
	v_exp_f32_e32 v89, v89
	s_and_b32 s3, s12, 0x3fffffc0
	s_lshl_b32 s3, s3, 2
	s_add_i32 s3, s3, 0
	s_add_i32 s3, s3, 0x10000
	s_waitcnt lgkmcnt(1)
	v_mfma_f32_32x32x16_bf16 v[122:137], v[0:3], v[162:165], v[122:137]
	v_bitop3_b32 v0, v170, v221, 64 bitop3:0x36
	s_waitcnt lgkmcnt(0)
	v_mfma_f32_32x32x16_bf16 v[106:121], v[4:7], v[162:165], v[106:121]
	v_add3_u32 v162, 0, v0, v228
	ds_read_b128 v[0:3], v162 offset:49152
	ds_read_b128 v[4:7], v162 offset:57344
	s_waitcnt lgkmcnt(1)
	v_mfma_f32_32x32x16_bf16 v[122:137], v[0:3], v[158:161], v[122:137]
	v_bitop3_b32 v0, v170, v221, s4 bitop3:0x36
	s_waitcnt lgkmcnt(0)
	v_mfma_f32_32x32x16_bf16 v[106:121], v[4:7], v[158:161], v[106:121]
	v_add3_u32 v158, 0, v0, v228
	ds_read_b128 v[0:3], v158 offset:49152
	ds_read_b128 v[4:7], v158 offset:57344
	s_waitcnt lgkmcnt(1)
	v_mfma_f32_32x32x16_bf16 v[122:137], v[0:3], v[154:157], v[122:137]
	s_waitcnt lgkmcnt(0)
	v_mfma_f32_32x32x16_bf16 v[106:121], v[4:7], v[154:157], v[106:121]
	ds_read_b128 v[0:3], v173 offset:49280
	ds_read_b128 v[4:7], v173 offset:57472
	s_waitcnt lgkmcnt(1)
	v_mfma_f32_32x32x16_bf16 v[122:137], v[0:3], v[150:153], v[122:137]
	s_waitcnt lgkmcnt(0)
	v_mfma_f32_32x32x16_bf16 v[106:121], v[4:7], v[150:153], v[106:121]
	ds_read_b128 v[0:3], v166 offset:49280
	ds_read_b128 v[4:7], v166 offset:57472
	s_waitcnt lgkmcnt(1)
	v_mfma_f32_32x32x16_bf16 v[122:137], v[0:3], v[146:149], v[122:137]
	s_waitcnt lgkmcnt(0)
	v_mfma_f32_32x32x16_bf16 v[106:121], v[4:7], v[146:149], v[106:121]
	ds_read_b128 v[0:3], v162 offset:49280
	ds_read_b128 v[4:7], v162 offset:57472
	s_waitcnt lgkmcnt(1)
	v_mfma_f32_32x32x16_bf16 v[122:137], v[0:3], v[142:145], v[122:137]
	s_waitcnt lgkmcnt(0)
	v_mfma_f32_32x32x16_bf16 v[106:121], v[4:7], v[142:145], v[106:121]
	ds_read_b128 v[0:3], v158 offset:49280
	ds_read_b128 v[4:7], v158 offset:57472
	s_waitcnt lgkmcnt(1)
	v_mfma_f32_32x32x16_bf16 v[122:137], v[0:3], v[138:141], v[122:137]
	v_exp_f32_e32 v1, v90
	v_exp_f32_e32 v3, v91
	v_exp_f32_e32 v90, v95
	v_exp_f32_e32 v91, v96
	v_add_f32_e32 v0, 0, v1
	v_add_f32_e32 v0, v3, v0
	v_exp_f32_e32 v95, v100
	s_waitcnt lgkmcnt(0)
	v_mfma_f32_32x32x16_bf16 v[106:121], v[4:7], v[138:141], v[106:121]
	v_exp_f32_e32 v5, v92
	v_exp_f32_e32 v6, v93
	v_exp_f32_e32 v7, v94
	v_exp_f32_e32 v92, v97
	v_add_f32_e32 v0, v5, v0
	v_add_f32_e32 v0, v6, v0
	v_exp_f32_e32 v93, v98
	v_add_f32_e32 v0, v7, v0
	v_exp_f32_e32 v94, v99
	v_add_f32_e32 v0, v90, v0
	v_add_f32_e32 v0, v91, v0
	v_exp_f32_e32 v96, v101
	v_add_f32_e32 v0, v92, v0
	v_exp_f32_e32 v97, v102
	v_add_f32_e32 v0, v93, v0
	v_exp_f32_e32 v98, v103
	v_add_f32_e32 v0, v94, v0
	v_exp_f32_e32 v99, v104
	v_add_f32_e32 v0, v95, v0
	v_exp_f32_e32 v100, v105
	v_add_f32_e32 v0, v96, v0
	v_exp_f32_e32 v101, v74
	v_add_f32_e32 v0, v97, v0
	v_exp_f32_e32 v102, v75
	v_add_f32_e32 v0, v98, v0
	v_exp_f32_e32 v103, v76
	v_add_f32_e32 v0, v99, v0
	v_exp_f32_e32 v104, v77
	v_add_f32_e32 v0, v100, v0
	v_exp_f32_e32 v105, v78
	v_add_f32_e32 v0, v101, v0
	v_exp_f32_e32 v138, v79
	v_add_f32_e32 v0, v102, v0
	v_exp_f32_e32 v139, v80
	v_add_f32_e32 v0, v103, v0
	v_add_f32_e32 v0, v104, v0
	v_add_f32_e32 v0, v105, v0
	v_add_f32_e32 v0, v138, v0
	v_add_f32_e32 v0, v139, v0
	v_add_f32_e32 v0, v81, v0
	v_add_f32_e32 v0, v82, v0
	v_add_f32_e32 v0, v83, v0
	v_add_f32_e32 v0, v84, v0
	v_add_f32_e32 v0, v85, v0
	v_add_f32_e32 v0, v86, v0
	v_add_f32_e32 v0, v87, v0
	v_add_f32_e32 v0, v88, v0
	v_add_f32_e32 v0, v89, v0
	v_mov_b32_e32 v2, v0
	s_nop 1
	v_permlane32_swap_b32_e32 v0, v2
	v_cvt_pk_bf16_f32 v4, v1, v3
	v_cvt_pk_bf16_f32 v5, v5, v6
	v_cvt_pk_bf16_f32 v6, v7, v90
	v_cvt_pk_bf16_f32 v7, v91, v92
	v_cvt_pk_bf16_f32 v74, v93, v94
	v_cvt_pk_bf16_f32 v75, v95, v96
	v_cvt_pk_bf16_f32 v76, v97, v98
	v_cvt_pk_bf16_f32 v77, v99, v100
	v_cvt_pk_bf16_f32 v78, v101, v102
	v_cvt_pk_bf16_f32 v79, v103, v104
	v_cvt_pk_bf16_f32 v80, v105, v138
	v_cvt_pk_bf16_f32 v81, v139, v81
	v_cvt_pk_bf16_f32 v82, v82, v83
	v_cvt_pk_bf16_f32 v83, v84, v85
	v_cvt_pk_bf16_f32 v84, v86, v87
	v_cvt_pk_bf16_f32 v85, v88, v89
	s_nop 0
	v_permlane32_swap_b32_e32 v4, v6
	v_permlane32_swap_b32_e32 v5, v7
	v_permlane32_swap_b32_e32 v74, v76
	v_permlane32_swap_b32_e32 v75, v77
	v_permlane32_swap_b32_e32 v78, v80
	v_permlane32_swap_b32_e32 v79, v81
	v_permlane32_swap_b32_e32 v82, v84
	v_permlane32_swap_b32_e32 v83, v85
	s_waitcnt lgkmcnt(0)
	ds_read_b64_tr_b16 v[86:87], v220 offset:0
	ds_read_b64_tr_b16 v[88:89], v220 offset:0x800
	ds_read_b64_tr_b16 v[90:91], v220 offset:0x1000
	ds_read_b64_tr_b16 v[92:93], v220 offset:0x1800
	ds_read_b64_tr_b16 v[94:95], v220 offset:0x2000
	ds_read_b64_tr_b16 v[96:97], v220 offset:0x2800
	ds_read_b64_tr_b16 v[98:99], v220 offset:0x3000
	ds_read_b64_tr_b16 v[100:101], v220 offset:0x3800
	s_waitcnt lgkmcnt(4)
; #define SBAR() __builtin_amdgcn_sched_barrier(0)
; #define PV_WAIT4() do { asm volatile("s_waitcnt lgkmcnt(4)" ::: "memory"); SBAR(); } while (0)
; #define PV_WAIT0() do { asm volatile("s_waitcnt lgkmcnt(0)" ::: "memory"); SBAR(); } while (0)
; #define PV_MM(od, pX, pY, g) do { od = __builtin_amdgcn_mfma_f32_32x32x16_bf16(pX, PK(g.l0, g.h0), od, 0, 0, 0); od = __builtin_amdgcn_mfma_f32_32x32x16_bf16(pY, PK(g.l1, g.h1), od, 0, 0, 0); } while (0)
; __device__ __forceinline__ void pv_d0(f32x16* o, int vb, bf16x8 pa0, bf16x8 pa1, bf16x8 pa2, bf16x8 pa3) {
;   asm volatile("s_waitcnt lgkmcnt(0)" ::: "memory");
;   VG a0 = pv_reads<0, 0>(vb), b0 = pv_reads<0, 2>(vb);
;   PV_WAIT4(); PV_MM(o[0], pa0, pa1, a0); VG a1 = pv_reads<1, 0>(vb);
;   PV_WAIT4(); PV_MM(o[0], pa2, pa3, b0); VG b1 = pv_reads<1, 2>(vb);
;   PV_WAIT4(); PV_MM(o[1], pa0, pa1, a1); VG a2 = pv_reads<2, 0>(vb);
;   PV_WAIT4(); PV_MM(o[1], pa2, pa3, b1); VG b2 = pv_reads<2, 2>(vb);
;   PV_WAIT4(); PV_MM(o[2], pa0, pa1, a2); VG a3 = pv_reads<3, 0>(vb);
;   PV_WAIT4(); PV_MM(o[2], pa2, pa3, b2); VG b3 = pv_reads<3, 2>(vb);
;   PV_WAIT4(); PV_MM(o[3], pa0, pa1, a3);
;   PV_WAIT0(); PV_MM(o[3], pa2, pa3, b3);
; }
; template <int J> ...
;     ...
;   pv_d0(o, vb0, pa0, pa1, pa2, pa3); SBAR();
;   __syncthreads();
;   finishSM(pB0, pB1, l_reg, pa0, pa1, pa2, pa3); SBAR();
;   pv_d0(o, vb0 + (int)SHM_V, pa0, pa1, pa2, pa3);
	s_nop 0
	v_mfma_f32_32x32x16_bf16 v[58:73], v[4:7], v[86:89], v[58:73]
	ds_read_b64_tr_b16 v[86:87], v220 offset:0x200
	ds_read_b64_tr_b16 v[88:89], v220 offset:0xa00
	v_mfma_f32_32x32x16_bf16 v[58:73], v[74:77], v[90:93], v[58:73]
	ds_read_b64_tr_b16 v[90:91], v220 offset:0x1200
	ds_read_b64_tr_b16 v[92:93], v220 offset:0x1a00
	s_waitcnt lgkmcnt(4)
	v_mfma_f32_32x32x16_bf16 v[58:73], v[78:81], v[94:97], v[58:73]
	ds_read_b64_tr_b16 v[94:95], v220 offset:0x2200
	ds_read_b64_tr_b16 v[96:97], v220 offset:0x2a00
	v_mfma_f32_32x32x16_bf16 v[58:73], v[82:85], v[98:101], v[58:73]
	ds_read_b64_tr_b16 v[98:99], v220 offset:0x3200
	ds_read_b64_tr_b16 v[100:101], v220 offset:0x3a00
	s_waitcnt lgkmcnt(4)
	v_mfma_f32_32x32x16_bf16 v[42:57], v[4:7], v[86:89], v[42:57]
	ds_read_b64_tr_b16 v[86:87], v220 offset:0x400
	ds_read_b64_tr_b16 v[88:89], v220 offset:0xc00
	v_mfma_f32_32x32x16_bf16 v[42:57], v[74:77], v[90:93], v[42:57]
	ds_read_b64_tr_b16 v[90:91], v220 offset:0x1400
	ds_read_b64_tr_b16 v[92:93], v220 offset:0x1c00
	s_waitcnt lgkmcnt(4)
	v_mfma_f32_32x32x16_bf16 v[42:57], v[78:81], v[94:97], v[42:57]
	ds_read_b64_tr_b16 v[94:95], v220 offset:0x2400
	ds_read_b64_tr_b16 v[96:97], v220 offset:0x2c00
	v_mfma_f32_32x32x16_bf16 v[42:57], v[82:85], v[98:101], v[42:57]
	ds_read_b64_tr_b16 v[98:99], v220 offset:0x3400
	ds_read_b64_tr_b16 v[100:101], v220 offset:0x3c00
	s_waitcnt lgkmcnt(4)
	v_mfma_f32_32x32x16_bf16 v[26:41], v[4:7], v[86:89], v[26:41]
	ds_read_b64_tr_b16 v[86:87], v220 offset:0x600
	ds_read_b64_tr_b16 v[88:89], v220 offset:0xe00
	v_mfma_f32_32x32x16_bf16 v[26:41], v[74:77], v[90:93], v[26:41]
	ds_read_b64_tr_b16 v[90:91], v220 offset:0x1600
	ds_read_b64_tr_b16 v[92:93], v220 offset:0x1e00
	s_waitcnt lgkmcnt(4)
	v_mfma_f32_32x32x16_bf16 v[26:41], v[78:81], v[94:97], v[26:41]
	ds_read_b64_tr_b16 v[94:95], v220 offset:0x2600
	ds_read_b64_tr_b16 v[96:97], v220 offset:0x2e00
	v_mfma_f32_32x32x16_bf16 v[26:41], v[82:85], v[98:101], v[26:41]
	ds_read_b64_tr_b16 v[98:99], v220 offset:0x3600
	ds_read_b64_tr_b16 v[100:101], v220 offset:0x3e00
	s_waitcnt lgkmcnt(4)
	v_mfma_f32_32x32x16_bf16 v[10:25], v[4:7], v[86:89], v[10:25]
	s_waitcnt lgkmcnt(0)
	v_mfma_f32_32x32x16_bf16 v[10:25], v[74:77], v[90:93], v[10:25]
	v_mfma_f32_32x32x16_bf16 v[10:25], v[78:81], v[94:97], v[10:25]
	v_mfma_f32_32x32x16_bf16 v[10:25], v[82:85], v[98:101], v[10:25]
	v_exp_f32_e32 v4, v122
	v_exp_f32_e32 v5, v123
	v_exp_f32_e32 v6, v124
	v_exp_f32_e32 v7, v125
	v_exp_f32_e32 v74, v126
	v_add_f32_e32 v1, 0, v4
	v_exp_f32_e32 v75, v127
	v_add_f32_e32 v1, v5, v1
	v_exp_f32_e32 v76, v128
	v_add_f32_e32 v1, v6, v1
	v_exp_f32_e32 v77, v129
	v_add_f32_e32 v1, v7, v1
	v_exp_f32_e32 v78, v130
	v_add_f32_e32 v1, v74, v1
	v_exp_f32_e32 v79, v131
	v_add_f32_e32 v1, v75, v1
	v_exp_f32_e32 v80, v132
	v_add_f32_e32 v1, v76, v1
	v_exp_f32_e32 v81, v133
	v_add_f32_e32 v1, v77, v1
	v_exp_f32_e32 v82, v134
	v_add_f32_e32 v1, v78, v1
	v_exp_f32_e32 v83, v135
	v_add_f32_e32 v1, v79, v1
	v_exp_f32_e32 v84, v136
	v_add_f32_e32 v1, v80, v1
	v_exp_f32_e32 v85, v137
	v_add_f32_e32 v1, v81, v1
	v_exp_f32_e32 v86, v106
	v_add_f32_e32 v1, v82, v1
	v_exp_f32_e32 v87, v107
	v_add_f32_e32 v1, v83, v1
	v_exp_f32_e32 v88, v108
	v_add_f32_e32 v1, v84, v1
	v_exp_f32_e32 v89, v109
	v_add_f32_e32 v1, v85, v1
	v_exp_f32_e32 v90, v110
	v_add_f32_e32 v1, v86, v1
	v_exp_f32_e32 v91, v111
	v_add_f32_e32 v1, v87, v1
	v_exp_f32_e32 v92, v112
	v_add_f32_e32 v1, v88, v1
	v_exp_f32_e32 v93, v113
	v_add_f32_e32 v1, v89, v1
	v_exp_f32_e32 v94, v114
	v_add_f32_e32 v1, v90, v1
	v_exp_f32_e32 v95, v115
	v_add_f32_e32 v1, v91, v1
	v_exp_f32_e32 v96, v116
	v_add_f32_e32 v1, v92, v1
	v_exp_f32_e32 v97, v117
	v_add_f32_e32 v1, v93, v1
	v_exp_f32_e32 v98, v118
	v_add_f32_e32 v1, v94, v1
	v_exp_f32_e32 v99, v119
	v_add_f32_e32 v1, v95, v1
	v_exp_f32_e32 v100, v120
	v_add_f32_e32 v1, v96, v1
	v_exp_f32_e32 v101, v121
	v_add_f32_e32 v1, v97, v1
	v_add_f32_e32 v1, v98, v1
	v_add_f32_e32 v1, v99, v1
	v_add_f32_e32 v1, v100, v1
	v_add_f32_e32 v1, v101, v1
	v_mov_b32_e32 v3, v1
	s_waitcnt vmcnt(0)
	s_barrier
	s_nop 0
	v_permlane32_swap_b32_e32 v1, v3
	v_cvt_pk_bf16_f32 v4, v4, v5
	v_cvt_pk_bf16_f32 v5, v6, v7
	v_cvt_pk_bf16_f32 v6, v74, v75
	v_cvt_pk_bf16_f32 v7, v76, v77
	v_cvt_pk_bf16_f32 v74, v78, v79
	v_cvt_pk_bf16_f32 v75, v80, v81
	v_cvt_pk_bf16_f32 v76, v82, v83
	v_cvt_pk_bf16_f32 v77, v84, v85
	v_cvt_pk_bf16_f32 v78, v86, v87
	v_cvt_pk_bf16_f32 v79, v88, v89
	v_cvt_pk_bf16_f32 v80, v90, v91
	v_cvt_pk_bf16_f32 v81, v92, v93
	v_cvt_pk_bf16_f32 v82, v94, v95
	v_cvt_pk_bf16_f32 v83, v96, v97
	v_cvt_pk_bf16_f32 v84, v98, v99
	v_cvt_pk_bf16_f32 v85, v100, v101
	s_nop 0
	v_permlane32_swap_b32_e32 v4, v6
	v_permlane32_swap_b32_e32 v5, v7
	v_permlane32_swap_b32_e32 v74, v76
	v_permlane32_swap_b32_e32 v75, v77
	v_permlane32_swap_b32_e32 v78, v80
	v_permlane32_swap_b32_e32 v79, v81
	v_permlane32_swap_b32_e32 v82, v84
	v_permlane32_swap_b32_e32 v83, v85
	s_cmp_lg_u32 0, -1
	s_cselect_b32 s4, 0, 0
	s_addk_i32 s4, 0x4000
	s_waitcnt lgkmcnt(0)
	v_add_u32_e32 v102, s4, v219
	ds_read_b64_tr_b16 v[86:87], v102 offset:0
	ds_read_b64_tr_b16 v[88:89], v102 offset:0x800
	ds_read_b64_tr_b16 v[90:91], v102 offset:0x1000
	ds_read_b64_tr_b16 v[92:93], v102 offset:0x1800
	ds_read_b64_tr_b16 v[94:95], v102 offset:0x2000
	ds_read_b64_tr_b16 v[96:97], v102 offset:0x2800
	ds_read_b64_tr_b16 v[98:99], v102 offset:0x3000
	ds_read_b64_tr_b16 v[100:101], v102 offset:0x3800
	s_waitcnt lgkmcnt(4)
; #define ATT_GAS __attribute__((address_space(1)))
; __device__ __forceinline__ int crow(int r, int hi) { return (r & 3) + 8 * (r >> 2) + 4 * hi; }
; __device__ __forceinline__ float bf2f(bf16 v) { return __uint_as_float((unsigned)v << 16); }
; __device__ __forceinline__ bf16 f2bf(float f) { unsigned u = __float_as_uint(f); return (bf16)((u + 0x7fffu + ((u >> 16) & 1u)) >> 16); }
; template <int J> ...
;     ...
;   pv_d0(o, vb0 + (int)SHM_V, pa0, pa1, pa2, pa3);
;   if (hi == 0) li_l[r32] = l_reg; asm volatile("s_waitcnt lgkmcnt(0)" ::: "memory");
;   float rli[16];
; #pragma unroll
;   for (int r = 0; r < 16; ++r) rli[r] = __builtin_amdgcn_rcpf(li_l[crow(r, hi)]);
;   bf16* Ow = Ob + (long)(wid * QBLK) * LD; const float lam = (J == 0) ? *(const float*)(lds + SHM_ATTN + 4) : 0.f;
; #pragma unroll
;   for (int r = 0; r < 16; ++r) { const int orow = crow(r, hi);
;     if (wid * QBLK + orow < nvalid) {
; #pragma unroll
;       for (int d0 = 0; d0 < 4; ++d0) { ATT_GAS bf16* p = (ATT_GAS bf16*)(Ow + (long)orow * LD + d0 * 32 + r32); const float v = o[d0][r] * rli[r];
;         if (J == 1) *p = f2bf(v); else *p = f2bf(v - lam * bf2f(*p)); } } }
	s_nop 0
	v_mfma_f32_32x32x16_bf16 v[58:73], v[4:7], v[86:89], v[58:73]
	ds_read_b64_tr_b16 v[86:87], v102 offset:0x200
	ds_read_b64_tr_b16 v[88:89], v102 offset:0xa00
	v_mfma_f32_32x32x16_bf16 v[58:73], v[74:77], v[90:93], v[58:73]
	ds_read_b64_tr_b16 v[90:91], v102 offset:0x1200
	ds_read_b64_tr_b16 v[92:93], v102 offset:0x1a00
	s_waitcnt lgkmcnt(4)
	v_mfma_f32_32x32x16_bf16 v[58:73], v[78:81], v[94:97], v[58:73]
	ds_read_b64_tr_b16 v[94:95], v102 offset:0x2200
	ds_read_b64_tr_b16 v[96:97], v102 offset:0x2a00
	v_mfma_f32_32x32x16_bf16 v[58:73], v[82:85], v[98:101], v[58:73]
	ds_read_b64_tr_b16 v[98:99], v102 offset:0x3200
	ds_read_b64_tr_b16 v[100:101], v102 offset:0x3a00
	s_waitcnt lgkmcnt(4)
	v_mfma_f32_32x32x16_bf16 v[42:57], v[4:7], v[86:89], v[42:57]
	ds_read_b64_tr_b16 v[86:87], v102 offset:0x400
	ds_read_b64_tr_b16 v[88:89], v102 offset:0xc00
	v_mfma_f32_32x32x16_bf16 v[42:57], v[74:77], v[90:93], v[42:57]
	ds_read_b64_tr_b16 v[90:91], v102 offset:0x1400
	ds_read_b64_tr_b16 v[92:93], v102 offset:0x1c00
	s_waitcnt lgkmcnt(4)
	v_mfma_f32_32x32x16_bf16 v[42:57], v[78:81], v[94:97], v[42:57]
	ds_read_b64_tr_b16 v[94:95], v102 offset:0x2400
	ds_read_b64_tr_b16 v[96:97], v102 offset:0x2c00
	v_mfma_f32_32x32x16_bf16 v[42:57], v[82:85], v[98:101], v[42:57]
	ds_read_b64_tr_b16 v[98:99], v102 offset:0x3400
	ds_read_b64_tr_b16 v[100:101], v102 offset:0x3c00
	s_waitcnt lgkmcnt(4)
	v_mfma_f32_32x32x16_bf16 v[26:41], v[4:7], v[86:89], v[26:41]
	ds_read_b64_tr_b16 v[86:87], v102 offset:0x600
	ds_read_b64_tr_b16 v[88:89], v102 offset:0xe00
	v_mfma_f32_32x32x16_bf16 v[26:41], v[74:77], v[90:93], v[26:41]
	ds_read_b64_tr_b16 v[90:91], v102 offset:0x1600
	ds_read_b64_tr_b16 v[92:93], v102 offset:0x1e00
	s_waitcnt lgkmcnt(4)
	v_mfma_f32_32x32x16_bf16 v[26:41], v[78:81], v[94:97], v[26:41]
	ds_read_b64_tr_b16 v[94:95], v102 offset:0x2600
	ds_read_b64_tr_b16 v[96:97], v102 offset:0x2e00
	v_mfma_f32_32x32x16_bf16 v[26:41], v[82:85], v[98:101], v[26:41]
	ds_read_b64_tr_b16 v[98:99], v102 offset:0x3600
	ds_read_b64_tr_b16 v[100:101], v102 offset:0x3e00
	s_waitcnt lgkmcnt(4)
	v_mfma_f32_32x32x16_bf16 v[10:25], v[4:7], v[86:89], v[10:25]
	s_waitcnt lgkmcnt(0)
	v_mfma_f32_32x32x16_bf16 v[10:25], v[74:77], v[90:93], v[10:25]
	v_mfma_f32_32x32x16_bf16 v[10:25], v[78:81], v[94:97], v[10:25]
	v_cmp_gt_u32_e32 vcc, 32, v9
	v_mfma_f32_32x32x16_bf16 v[10:25], v[82:85], v[98:101], v[10:25]
	s_and_saveexec_b64 s[4:5], vcc
	v_pk_add_f32 v[0:1], v[0:1], v[2:3]
	v_lshl_add_u32 v4, v218, 2, s3
	v_add_f32_e32 v0, v227, v0
	v_add_f32_e32 v0, v0, v1
	ds_write_b32 v4, v0
	s_or_b64 exec, exec, s[4:5]
	s_ashr_i32 s23, s22, 31
	v_lshl_add_u32 v78, v216, 2, s3
	s_lshl_b64 s[4:5], s[22:23], 12
	v_readlane_b32 s3, v244, 7
	s_waitcnt lgkmcnt(0)
	s_add_u32 s4, s3, s4
	v_readlane_b32 s3, v244, 10
	ds_read2_b32 v[82:83], v78 offset0:1 offset1:2
	ds_read_b32 v9, v78 offset:12
	ds_read_b128 v[74:77], v78 offset:32
	ds_read_b128 v[4:7], v78 offset:64
	s_addc_u32 s5, s3, s5
	v_readlane_b32 s3, v244, 32
	v_lshlrev_b32_e32 v170, 1, v218
	v_or_b32_e32 v84, s22, v216
	v_mov_b32_e32 v79, s3
	ds_read_b128 v[0:3], v78 offset:96
	ds_read_b32 v79, v79
	v_lshl_add_u64 v[80:81], s[4:5], 0, v[170:171]
	v_cmp_gt_i32_e32 vcc, s8, v84
	s_and_saveexec_b64 s[4:5], vcc
	s_cbranch_execz .LBB0_712
	v_lshlrev_b32_e32 v170, 14, v217
	v_lshl_add_u64 v[84:85], v[80:81], 0, v[170:171]
	global_load_ushort v86, v[84:85], off
	global_load_ushort v249, v[84:85], off offset:64
	global_load_ushort v250, v[84:85], off offset:128
	global_load_ushort v251, v[84:85], off offset:192
	ds_read_b32 v78, v78
	s_waitcnt lgkmcnt(0)
	v_rcp_f32_e32 v78, v78
	s_waitcnt vmcnt(3)
	v_lshlrev_b32_e32 v86, 16, v86
	v_mul_f32_e32 v86, v79, v86
	v_fma_f32 v58, v58, v78, -v86
	v_bfe_u32 v86, v58, 16, 1
	v_add3_u32 v58, v58, v86, s26
	global_store_short_d16_hi v[84:85], v58, off
	s_waitcnt vmcnt(3)
	v_mov_b32_e32 v58, v249
	v_lshlrev_b32_e32 v58, 16, v58
	v_mul_f32_e32 v58, v79, v58
	v_fma_f32 v42, v42, v78, -v58
	v_bfe_u32 v58, v42, 16, 1
	v_add3_u32 v42, v42, v58, s26
	global_store_short_d16_hi v[84:85], v42, off offset:64
	s_waitcnt vmcnt(3)
	v_mov_b32_e32 v42, v250
	v_lshlrev_b32_e32 v42, 16, v42
	v_mul_f32_e32 v42, v79, v42
	v_fma_f32 v26, v26, v78, -v42
	v_bfe_u32 v42, v26, 16, 1
	v_add3_u32 v26, v26, v42, s26
	global_store_short_d16_hi v[84:85], v26, off offset:128
	s_waitcnt vmcnt(3)
	v_mov_b32_e32 v26, v251
	v_lshlrev_b32_e32 v26, 16, v26
	v_mul_f32_e32 v26, v79, v26
	v_fma_f32 v10, v10, v78, -v26
	v_bfe_u32 v26, v10, 16, 1
	v_add3_u32 v10, v10, v26, s26
	global_store_short_d16_hi v[84:85], v10, off offset:192
.LBB0_712:
	s_or_b64 exec, exec, s[4:5]
	v_or_b32_e32 v10, 1, v216
	v_or_b32_e32 v26, s22, v10
	v_cmp_gt_i32_e32 vcc, s8, v26
	s_and_saveexec_b64 s[4:5], vcc
	s_cbranch_execz .LBB0_714
	v_lshlrev_b32_e32 v170, 12, v10
	v_lshl_add_u64 v[84:85], v[80:81], 0, v[170:171]
	global_load_ushort v10, v[84:85], off
	global_load_ushort v249, v[84:85], off offset:64
	global_load_ushort v250, v[84:85], off offset:128
	global_load_ushort v251, v[84:85], off offset:192
	s_waitcnt lgkmcnt(5)
	v_rcp_f32_e32 v26, v82
	s_waitcnt vmcnt(3)
	v_lshlrev_b32_e32 v10, 16, v10
	s_waitcnt lgkmcnt(0)
	v_mul_f32_e32 v10, v79, v10
	v_fma_f32 v10, v59, v26, -v10
	v_bfe_u32 v42, v10, 16, 1
	v_add3_u32 v10, v10, v42, s26
	global_store_short_d16_hi v[84:85], v10, off
	s_waitcnt vmcnt(3)
	v_mov_b32_e32 v10, v249
	v_lshlrev_b32_e32 v10, 16, v10
	v_mul_f32_e32 v10, v79, v10
	v_fma_f32 v10, v43, v26, -v10
	v_bfe_u32 v42, v10, 16, 1
	v_add3_u32 v10, v10, v42, s26
	global_store_short_d16_hi v[84:85], v10, off offset:64
	s_waitcnt vmcnt(3)
	v_mov_b32_e32 v10, v250
	v_lshlrev_b32_e32 v10, 16, v10
	v_mul_f32_e32 v10, v79, v10
	v_fma_f32 v10, v27, v26, -v10
	v_bfe_u32 v27, v10, 16, 1
	v_add3_u32 v10, v10, v27, s26
	global_store_short_d16_hi v[84:85], v10, off offset:128
	s_waitcnt vmcnt(3)
	v_mov_b32_e32 v10, v251
	v_lshlrev_b32_e32 v10, 16, v10
	v_mul_f32_e32 v10, v79, v10
	v_fma_f32 v10, v11, v26, -v10
	v_bfe_u32 v11, v10, 16, 1
	v_add3_u32 v10, v10, v11, s26
	global_store_short_d16_hi v[84:85], v10, off offset:192
; #define ATT_GAS __attribute__((address_space(1)))
; __device__ __forceinline__ int crow(int r, int hi) { return (r & 3) + 8 * (r >> 2) + 4 * hi; }
; __device__ __forceinline__ float bf2f(bf16 v) { return __uint_as_float((unsigned)v << 16); }
; __device__ __forceinline__ bf16 f2bf(float f) { unsigned u = __float_as_uint(f); return (bf16)((u + 0x7fffu + ((u >> 16) & 1u)) >> 16); }
; template <int J> ...
;     ...
;   for (int r = 0; r < 16; ++r) { const int orow = crow(r, hi);
;     if (wid * QBLK + orow < nvalid) {
; #pragma unroll
;       for (int d0 = 0; d0 < 4; ++d0) { ATT_GAS bf16* p = (ATT_GAS bf16*)(Ow + (long)orow * LD + d0 * 32 + r32); const float v = o[d0][r] * rli[r];
;         if (J == 1) *p = f2bf(v); else *p = f2bf(v - lam * bf2f(*p)); } } }
.LBB0_714:
	s_or_b64 exec, exec, s[4:5]
	v_or_b32_e32 v10, 2, v216
	v_or_b32_e32 v11, s22, v10
	v_cmp_gt_i32_e32 vcc, s8, v11
	s_and_saveexec_b64 s[4:5], vcc
	s_cbranch_execz .LBB0_716
	v_lshlrev_b32_e32 v170, 12, v10
	v_lshl_add_u64 v[10:11], v[80:81], 0, v[170:171]
	global_load_ushort v27, v[10:11], off
	global_load_ushort v249, v[10:11], off offset:64
	global_load_ushort v250, v[10:11], off offset:128
	global_load_ushort v251, v[10:11], off offset:192
	s_waitcnt lgkmcnt(5)
	v_rcp_f32_e32 v26, v83
	s_waitcnt vmcnt(3)
	v_lshlrev_b32_e32 v27, 16, v27
	s_waitcnt lgkmcnt(0)
	v_mul_f32_e32 v27, v79, v27
	v_fma_f32 v27, v60, v26, -v27
	v_bfe_u32 v42, v27, 16, 1
	v_add3_u32 v27, v27, v42, s26
	global_store_short_d16_hi v[10:11], v27, off
	s_waitcnt vmcnt(3)
	v_mov_b32_e32 v27, v249
	v_lshlrev_b32_e32 v27, 16, v27
	v_mul_f32_e32 v27, v79, v27
	v_fma_f32 v27, v44, v26, -v27
	v_bfe_u32 v42, v27, 16, 1
	v_add3_u32 v27, v27, v42, s26
	global_store_short_d16_hi v[10:11], v27, off offset:64
	s_waitcnt vmcnt(3)
	v_mov_b32_e32 v27, v250
	v_lshlrev_b32_e32 v27, 16, v27
	v_mul_f32_e32 v27, v79, v27
	v_fma_f32 v27, v28, v26, -v27
	v_bfe_u32 v28, v27, 16, 1
	v_add3_u32 v27, v27, v28, s26
	global_store_short_d16_hi v[10:11], v27, off offset:128
	s_waitcnt vmcnt(3)
	v_mov_b32_e32 v27, v251
	v_lshlrev_b32_e32 v27, 16, v27
	v_mul_f32_e32 v27, v79, v27
	v_fma_f32 v12, v12, v26, -v27
	v_bfe_u32 v26, v12, 16, 1
	v_add3_u32 v12, v12, v26, s26
	global_store_short_d16_hi v[10:11], v12, off offset:192
.LBB0_716:
	s_or_b64 exec, exec, s[4:5]
	v_or_b32_e32 v10, 3, v216
	v_or_b32_e32 v11, s22, v10
	v_cmp_gt_i32_e32 vcc, s8, v11
	s_and_saveexec_b64 s[4:5], vcc
	s_cbranch_execz .LBB0_718
	v_lshlrev_b32_e32 v170, 12, v10
	v_lshl_add_u64 v[10:11], v[80:81], 0, v[170:171]
	global_load_ushort v12, v[10:11], off
	global_load_ushort v249, v[10:11], off offset:64
	global_load_ushort v250, v[10:11], off offset:128
	global_load_ushort v251, v[10:11], off offset:192
	s_waitcnt lgkmcnt(4)
	v_rcp_f32_e32 v9, v9
	s_waitcnt vmcnt(3)
	v_lshlrev_b32_e32 v12, 16, v12
	s_waitcnt lgkmcnt(0)
	v_mul_f32_e32 v12, v79, v12
	v_fma_f32 v12, v61, v9, -v12
	v_bfe_u32 v26, v12, 16, 1
	v_add3_u32 v12, v12, v26, s26
	global_store_short_d16_hi v[10:11], v12, off
	s_waitcnt vmcnt(3)
	v_mov_b32_e32 v12, v249
	v_lshlrev_b32_e32 v12, 16, v12
	v_mul_f32_e32 v12, v79, v12
	v_fma_f32 v12, v45, v9, -v12
	v_bfe_u32 v26, v12, 16, 1
	v_add3_u32 v12, v12, v26, s26
	global_store_short_d16_hi v[10:11], v12, off offset:64
	s_waitcnt vmcnt(3)
	v_mov_b32_e32 v12, v250
	v_lshlrev_b32_e32 v12, 16, v12
	v_mul_f32_e32 v12, v79, v12
	v_fma_f32 v12, v29, v9, -v12
	v_bfe_u32 v26, v12, 16, 1
	v_add3_u32 v12, v12, v26, s26
	global_store_short_d16_hi v[10:11], v12, off offset:128
	s_waitcnt vmcnt(3)
	v_mov_b32_e32 v12, v251
	v_lshlrev_b32_e32 v12, 16, v12
	v_mul_f32_e32 v12, v79, v12
	v_fma_f32 v9, v13, v9, -v12
	v_bfe_u32 v12, v9, 16, 1
	v_add3_u32 v9, v9, v12, s26
	global_store_short_d16_hi v[10:11], v9, off offset:192
.LBB0_718:
	s_or_b64 exec, exec, s[4:5]
	s_waitcnt lgkmcnt(4)
	v_or_b32_e32 v9, 8, v216
	v_or_b32_e32 v10, s22, v9
	v_cmp_gt_i32_e32 vcc, s8, v10
	s_and_saveexec_b64 s[4:5], vcc
	s_cbranch_execz .LBB0_720
	v_lshlrev_b32_e32 v170, 12, v9
	v_lshl_add_u64 v[10:11], v[80:81], 0, v[170:171]
	global_load_ushort v9, v[10:11], off
	global_load_ushort v249, v[10:11], off offset:64
	global_load_ushort v250, v[10:11], off offset:128
	global_load_ushort v251, v[10:11], off offset:192
	s_waitcnt lgkmcnt(3)
	v_rcp_f32_e32 v12, v74
	s_waitcnt vmcnt(3)
	v_lshlrev_b32_e32 v9, 16, v9
	s_waitcnt lgkmcnt(0)
	v_mul_f32_e32 v9, v79, v9
	v_fma_f32 v9, v62, v12, -v9
	v_bfe_u32 v13, v9, 16, 1
	v_add3_u32 v9, v9, v13, s26
	global_store_short_d16_hi v[10:11], v9, off
	s_waitcnt vmcnt(3)
	v_mov_b32_e32 v9, v249
	v_lshlrev_b32_e32 v9, 16, v9
	v_mul_f32_e32 v9, v79, v9
	v_fma_f32 v9, v46, v12, -v9
	v_bfe_u32 v13, v9, 16, 1
	v_add3_u32 v9, v9, v13, s26
	global_store_short_d16_hi v[10:11], v9, off offset:64
	s_waitcnt vmcnt(3)
	v_mov_b32_e32 v9, v250
	v_lshlrev_b32_e32 v9, 16, v9
	v_mul_f32_e32 v9, v79, v9
	v_fma_f32 v9, v30, v12, -v9
	v_bfe_u32 v13, v9, 16, 1
	v_add3_u32 v9, v9, v13, s26
	global_store_short_d16_hi v[10:11], v9, off offset:128
	s_waitcnt vmcnt(3)
	v_mov_b32_e32 v9, v251
	v_lshlrev_b32_e32 v9, 16, v9
	v_mul_f32_e32 v9, v79, v9
	v_fma_f32 v9, v14, v12, -v9
	v_bfe_u32 v12, v9, 16, 1
	v_add3_u32 v9, v9, v12, s26
	global_store_short_d16_hi v[10:11], v9, off offset:192
.LBB0_720:
	s_or_b64 exec, exec, s[4:5]
	v_or_b32_e32 v9, 9, v216
	v_or_b32_e32 v10, s22, v9
	v_cmp_gt_i32_e32 vcc, s8, v10
	s_and_saveexec_b64 s[4:5], vcc
	s_cbranch_execz .LBB0_722
	v_lshlrev_b32_e32 v170, 12, v9
	v_lshl_add_u64 v[10:11], v[80:81], 0, v[170:171]
	global_load_ushort v9, v[10:11], off
	global_load_ushort v249, v[10:11], off offset:64
	global_load_ushort v250, v[10:11], off offset:128
	global_load_ushort v251, v[10:11], off offset:192
	s_waitcnt lgkmcnt(3)
	v_rcp_f32_e32 v12, v75
	s_waitcnt vmcnt(3)
	v_lshlrev_b32_e32 v9, 16, v9
	s_waitcnt lgkmcnt(0)
	v_mul_f32_e32 v9, v79, v9
	v_fma_f32 v9, v63, v12, -v9
	v_bfe_u32 v13, v9, 16, 1
	v_add3_u32 v9, v9, v13, s26
	global_store_short_d16_hi v[10:11], v9, off
	s_waitcnt vmcnt(3)
	v_mov_b32_e32 v9, v249
	v_lshlrev_b32_e32 v9, 16, v9
	v_mul_f32_e32 v9, v79, v9
	v_fma_f32 v9, v47, v12, -v9
	v_bfe_u32 v13, v9, 16, 1
	v_add3_u32 v9, v9, v13, s26
	global_store_short_d16_hi v[10:11], v9, off offset:64
	s_waitcnt vmcnt(3)
	v_mov_b32_e32 v9, v250
	v_lshlrev_b32_e32 v9, 16, v9
	v_mul_f32_e32 v9, v79, v9
	v_fma_f32 v9, v31, v12, -v9
	v_bfe_u32 v13, v9, 16, 1
	v_add3_u32 v9, v9, v13, s26
	global_store_short_d16_hi v[10:11], v9, off offset:128
	s_waitcnt vmcnt(3)
	v_mov_b32_e32 v9, v251
	v_lshlrev_b32_e32 v9, 16, v9
	v_mul_f32_e32 v9, v79, v9
	v_fma_f32 v9, v15, v12, -v9
	v_bfe_u32 v12, v9, 16, 1
	v_add3_u32 v9, v9, v12, s26
	global_store_short_d16_hi v[10:11], v9, off offset:192
; #define ATT_GAS __attribute__((address_space(1)))
; __device__ __forceinline__ int crow(int r, int hi) { return (r & 3) + 8 * (r >> 2) + 4 * hi; }
; __device__ __forceinline__ float bf2f(bf16 v) { return __uint_as_float((unsigned)v << 16); }
; __device__ __forceinline__ bf16 f2bf(float f) { unsigned u = __float_as_uint(f); return (bf16)((u + 0x7fffu + ((u >> 16) & 1u)) >> 16); }
; template <int J> ...
;     ...
;   for (int r = 0; r < 16; ++r) { const int orow = crow(r, hi);
;     if (wid * QBLK + orow < nvalid) {
; #pragma unroll
;       for (int d0 = 0; d0 < 4; ++d0) { ATT_GAS bf16* p = (ATT_GAS bf16*)(Ow + (long)orow * LD + d0 * 32 + r32); const float v = o[d0][r] * rli[r];
;         if (J == 1) *p = f2bf(v); else *p = f2bf(v - lam * bf2f(*p)); } } }
.LBB0_722:
	s_or_b64 exec, exec, s[4:5]
	v_or_b32_e32 v9, 10, v216
	v_or_b32_e32 v10, s22, v9
	v_cmp_gt_i32_e32 vcc, s8, v10
	s_and_saveexec_b64 s[4:5], vcc
	s_cbranch_execz .LBB0_724
	v_lshlrev_b32_e32 v170, 12, v9
	v_lshl_add_u64 v[10:11], v[80:81], 0, v[170:171]
	global_load_ushort v9, v[10:11], off
	global_load_ushort v249, v[10:11], off offset:64
	global_load_ushort v250, v[10:11], off offset:128
	global_load_ushort v251, v[10:11], off offset:192
	s_waitcnt lgkmcnt(3)
	v_rcp_f32_e32 v12, v76
	s_waitcnt vmcnt(3)
	v_lshlrev_b32_e32 v9, 16, v9
	s_waitcnt lgkmcnt(0)
	v_mul_f32_e32 v9, v79, v9
	v_fma_f32 v9, v64, v12, -v9
	v_bfe_u32 v13, v9, 16, 1
	v_add3_u32 v9, v9, v13, s26
	global_store_short_d16_hi v[10:11], v9, off
	s_waitcnt vmcnt(3)
	v_mov_b32_e32 v9, v249
	v_lshlrev_b32_e32 v9, 16, v9
	v_mul_f32_e32 v9, v79, v9
	v_fma_f32 v9, v48, v12, -v9
	v_bfe_u32 v13, v9, 16, 1
	v_add3_u32 v9, v9, v13, s26
	global_store_short_d16_hi v[10:11], v9, off offset:64
	s_waitcnt vmcnt(3)
	v_mov_b32_e32 v9, v250
	v_lshlrev_b32_e32 v9, 16, v9
	v_mul_f32_e32 v9, v79, v9
	v_fma_f32 v9, v32, v12, -v9
	v_bfe_u32 v13, v9, 16, 1
	v_add3_u32 v9, v9, v13, s26
	global_store_short_d16_hi v[10:11], v9, off offset:128
	s_waitcnt vmcnt(3)
	v_mov_b32_e32 v9, v251
	v_lshlrev_b32_e32 v9, 16, v9
	v_mul_f32_e32 v9, v79, v9
	v_fma_f32 v9, v16, v12, -v9
	v_bfe_u32 v12, v9, 16, 1
	v_add3_u32 v9, v9, v12, s26
	global_store_short_d16_hi v[10:11], v9, off offset:192
.LBB0_724:
	s_or_b64 exec, exec, s[4:5]
	v_or_b32_e32 v9, 11, v216
	v_or_b32_e32 v10, s22, v9
	v_cmp_gt_i32_e32 vcc, s8, v10
	s_and_saveexec_b64 s[4:5], vcc
	s_cbranch_execz .LBB0_726
	v_lshlrev_b32_e32 v170, 12, v9
	v_lshl_add_u64 v[10:11], v[80:81], 0, v[170:171]
	global_load_ushort v9, v[10:11], off
	global_load_ushort v249, v[10:11], off offset:64
	global_load_ushort v250, v[10:11], off offset:128
	global_load_ushort v251, v[10:11], off offset:192
	s_waitcnt lgkmcnt(3)
	v_rcp_f32_e32 v12, v77
	s_waitcnt vmcnt(3)
	v_lshlrev_b32_e32 v9, 16, v9
	s_waitcnt lgkmcnt(0)
	v_mul_f32_e32 v9, v79, v9
	v_fma_f32 v9, v65, v12, -v9
	v_bfe_u32 v13, v9, 16, 1
	v_add3_u32 v9, v9, v13, s26
	global_store_short_d16_hi v[10:11], v9, off
	s_waitcnt vmcnt(3)
	v_mov_b32_e32 v9, v249
	v_lshlrev_b32_e32 v9, 16, v9
	v_mul_f32_e32 v9, v79, v9
	v_fma_f32 v9, v49, v12, -v9
	v_bfe_u32 v13, v9, 16, 1
	v_add3_u32 v9, v9, v13, s26
	global_store_short_d16_hi v[10:11], v9, off offset:64
	s_waitcnt vmcnt(3)
	v_mov_b32_e32 v9, v250
	v_lshlrev_b32_e32 v9, 16, v9
	v_mul_f32_e32 v9, v79, v9
	v_fma_f32 v9, v33, v12, -v9
	v_bfe_u32 v13, v9, 16, 1
	v_add3_u32 v9, v9, v13, s26
	global_store_short_d16_hi v[10:11], v9, off offset:128
	s_waitcnt vmcnt(3)
	v_mov_b32_e32 v9, v251
	v_lshlrev_b32_e32 v9, 16, v9
	v_mul_f32_e32 v9, v79, v9
	v_fma_f32 v9, v17, v12, -v9
	v_bfe_u32 v12, v9, 16, 1
	v_add3_u32 v9, v9, v12, s26
	global_store_short_d16_hi v[10:11], v9, off offset:192
.LBB0_726:
	s_or_b64 exec, exec, s[4:5]
	v_or_b32_e32 v9, 16, v216
	v_or_b32_e32 v10, s22, v9
	v_cmp_gt_i32_e32 vcc, s8, v10
	s_and_saveexec_b64 s[4:5], vcc
	s_cbranch_execz .LBB0_728
	v_lshlrev_b32_e32 v170, 12, v9
	v_lshl_add_u64 v[10:11], v[80:81], 0, v[170:171]
	global_load_ushort v9, v[10:11], off
	global_load_ushort v249, v[10:11], off offset:64
	global_load_ushort v250, v[10:11], off offset:128
	global_load_ushort v251, v[10:11], off offset:192
	s_waitcnt lgkmcnt(2)
	v_rcp_f32_e32 v4, v4
	s_waitcnt vmcnt(3)
	v_lshlrev_b32_e32 v9, 16, v9
	s_waitcnt lgkmcnt(0)
	v_mul_f32_e32 v9, v79, v9
	v_fma_f32 v9, v66, v4, -v9
	v_bfe_u32 v12, v9, 16, 1
	v_add3_u32 v9, v9, v12, s26
	global_store_short_d16_hi v[10:11], v9, off
	s_waitcnt vmcnt(3)
	v_mov_b32_e32 v9, v249
	v_lshlrev_b32_e32 v9, 16, v9
	v_mul_f32_e32 v9, v79, v9
	v_fma_f32 v9, v50, v4, -v9
	v_bfe_u32 v12, v9, 16, 1
	v_add3_u32 v9, v9, v12, s26
	global_store_short_d16_hi v[10:11], v9, off offset:64
	s_waitcnt vmcnt(3)
	v_mov_b32_e32 v9, v250
	v_lshlrev_b32_e32 v9, 16, v9
	v_mul_f32_e32 v9, v79, v9
	v_fma_f32 v9, v34, v4, -v9
	v_bfe_u32 v12, v9, 16, 1
	v_add3_u32 v9, v9, v12, s26
	global_store_short_d16_hi v[10:11], v9, off offset:128
	s_waitcnt vmcnt(3)
	v_mov_b32_e32 v9, v251
	v_lshlrev_b32_e32 v9, 16, v9
	v_mul_f32_e32 v9, v79, v9
	v_fma_f32 v4, v18, v4, -v9
	v_bfe_u32 v9, v4, 16, 1
	v_add3_u32 v4, v4, v9, s26
	global_store_short_d16_hi v[10:11], v4, off offset:192
.LBB0_728:
	s_or_b64 exec, exec, s[4:5]
	s_waitcnt lgkmcnt(2)
	v_or_b32_e32 v4, 17, v216
	v_or_b32_e32 v9, s22, v4
	v_cmp_gt_i32_e32 vcc, s8, v9
	s_and_saveexec_b64 s[4:5], vcc
	s_cbranch_execz .LBB0_730
	v_lshlrev_b32_e32 v170, 12, v4
	v_rcp_f32_e32 v9, v5
	v_lshl_add_u64 v[4:5], v[80:81], 0, v[170:171]
	global_load_ushort v10, v[4:5], off
	global_load_ushort v249, v[4:5], off offset:64
	global_load_ushort v250, v[4:5], off offset:128
	global_load_ushort v251, v[4:5], off offset:192
	s_waitcnt vmcnt(3)
	v_lshlrev_b32_e32 v10, 16, v10
	s_waitcnt lgkmcnt(0)
	v_mul_f32_e32 v10, v79, v10
	v_fma_f32 v10, v67, v9, -v10
	v_bfe_u32 v11, v10, 16, 1
	v_add3_u32 v10, v10, v11, s26
	global_store_short_d16_hi v[4:5], v10, off
	s_waitcnt vmcnt(3)
	v_mov_b32_e32 v10, v249
	v_lshlrev_b32_e32 v10, 16, v10
	v_mul_f32_e32 v10, v79, v10
	v_fma_f32 v10, v51, v9, -v10
	v_bfe_u32 v11, v10, 16, 1
	v_add3_u32 v10, v10, v11, s26
	global_store_short_d16_hi v[4:5], v10, off offset:64
	s_waitcnt vmcnt(3)
	v_mov_b32_e32 v10, v250
	v_lshlrev_b32_e32 v10, 16, v10
	v_mul_f32_e32 v10, v79, v10
	v_fma_f32 v10, v35, v9, -v10
	v_bfe_u32 v11, v10, 16, 1
	v_add3_u32 v10, v10, v11, s26
	global_store_short_d16_hi v[4:5], v10, off offset:128
	s_waitcnt vmcnt(3)
	v_mov_b32_e32 v10, v251
	v_lshlrev_b32_e32 v10, 16, v10
	v_mul_f32_e32 v10, v79, v10
	v_fma_f32 v9, v19, v9, -v10
	v_bfe_u32 v10, v9, 16, 1
	v_add3_u32 v9, v9, v10, s26
	global_store_short_d16_hi v[4:5], v9, off offset:192
; #define ATT_GAS __attribute__((address_space(1)))
; __device__ __forceinline__ int crow(int r, int hi) { return (r & 3) + 8 * (r >> 2) + 4 * hi; }
; __device__ __forceinline__ float bf2f(bf16 v) { return __uint_as_float((unsigned)v << 16); }
; __device__ __forceinline__ bf16 f2bf(float f) { unsigned u = __float_as_uint(f); return (bf16)((u + 0x7fffu + ((u >> 16) & 1u)) >> 16); }
; template <int J> ...
;     ...
;   for (int r = 0; r < 16; ++r) { const int orow = crow(r, hi);
;     if (wid * QBLK + orow < nvalid) {
; #pragma unroll
;       for (int d0 = 0; d0 < 4; ++d0) { ATT_GAS bf16* p = (ATT_GAS bf16*)(Ow + (long)orow * LD + d0 * 32 + r32); const float v = o[d0][r] * rli[r];
;         if (J == 1) *p = f2bf(v); else *p = f2bf(v - lam * bf2f(*p)); } } }
.LBB0_730:
	s_or_b64 exec, exec, s[4:5]
	v_or_b32_e32 v4, 18, v216
	v_or_b32_e32 v5, s22, v4
	v_cmp_gt_i32_e32 vcc, s8, v5
	s_and_saveexec_b64 s[4:5], vcc
	s_cbranch_execz .LBB0_732
	v_lshlrev_b32_e32 v170, 12, v4
	v_lshl_add_u64 v[4:5], v[80:81], 0, v[170:171]
	global_load_ushort v9, v[4:5], off
	global_load_ushort v249, v[4:5], off offset:64
	global_load_ushort v250, v[4:5], off offset:128
	global_load_ushort v251, v[4:5], off offset:192
	v_rcp_f32_e32 v6, v6
	s_waitcnt vmcnt(3)
	v_lshlrev_b32_e32 v9, 16, v9
	s_waitcnt lgkmcnt(0)
	v_mul_f32_e32 v9, v79, v9
	v_fma_f32 v9, v68, v6, -v9
	v_bfe_u32 v10, v9, 16, 1
	v_add3_u32 v9, v9, v10, s26
	global_store_short_d16_hi v[4:5], v9, off
	s_waitcnt vmcnt(3)
	v_mov_b32_e32 v9, v249
	v_lshlrev_b32_e32 v9, 16, v9
	v_mul_f32_e32 v9, v79, v9
	v_fma_f32 v9, v52, v6, -v9
	v_bfe_u32 v10, v9, 16, 1
	v_add3_u32 v9, v9, v10, s26
	global_store_short_d16_hi v[4:5], v9, off offset:64
	s_waitcnt vmcnt(3)
	v_mov_b32_e32 v9, v250
	v_lshlrev_b32_e32 v9, 16, v9
	v_mul_f32_e32 v9, v79, v9
	v_fma_f32 v9, v36, v6, -v9
	v_bfe_u32 v10, v9, 16, 1
	v_add3_u32 v9, v9, v10, s26
	global_store_short_d16_hi v[4:5], v9, off offset:128
	s_waitcnt vmcnt(3)
	v_mov_b32_e32 v9, v251
	v_lshlrev_b32_e32 v9, 16, v9
	v_mul_f32_e32 v9, v79, v9
	v_fma_f32 v6, v20, v6, -v9
	v_bfe_u32 v9, v6, 16, 1
	v_add3_u32 v6, v6, v9, s26
	global_store_short_d16_hi v[4:5], v6, off offset:192
.LBB0_732:
	s_or_b64 exec, exec, s[4:5]
	v_or_b32_e32 v4, 19, v216
	v_or_b32_e32 v5, s22, v4
	v_cmp_gt_i32_e32 vcc, s8, v5
	s_and_saveexec_b64 s[4:5], vcc
	s_cbranch_execz .LBB0_734
	v_lshlrev_b32_e32 v170, 12, v4
	v_lshl_add_u64 v[4:5], v[80:81], 0, v[170:171]
	v_rcp_f32_e32 v6, v7
	global_load_ushort v7, v[4:5], off
	global_load_ushort v249, v[4:5], off offset:64
	global_load_ushort v250, v[4:5], off offset:128
	global_load_ushort v251, v[4:5], off offset:192
	s_waitcnt vmcnt(3)
	v_lshlrev_b32_e32 v7, 16, v7
	s_waitcnt lgkmcnt(0)
	v_mul_f32_e32 v7, v79, v7
	v_fma_f32 v7, v69, v6, -v7
	v_bfe_u32 v9, v7, 16, 1
	v_add3_u32 v7, v7, v9, s26
	global_store_short_d16_hi v[4:5], v7, off
	s_waitcnt vmcnt(3)
	v_mov_b32_e32 v7, v249
	v_lshlrev_b32_e32 v7, 16, v7
	v_mul_f32_e32 v7, v79, v7
	v_fma_f32 v7, v53, v6, -v7
	v_bfe_u32 v9, v7, 16, 1
	v_add3_u32 v7, v7, v9, s26
	global_store_short_d16_hi v[4:5], v7, off offset:64
	s_waitcnt vmcnt(3)
	v_mov_b32_e32 v7, v250
	v_lshlrev_b32_e32 v7, 16, v7
	v_mul_f32_e32 v7, v79, v7
	v_fma_f32 v7, v37, v6, -v7
	v_bfe_u32 v9, v7, 16, 1
	v_add3_u32 v7, v7, v9, s26
	global_store_short_d16_hi v[4:5], v7, off offset:128
	s_waitcnt vmcnt(3)
	v_mov_b32_e32 v7, v251
	v_lshlrev_b32_e32 v7, 16, v7
	v_mul_f32_e32 v7, v79, v7
	v_fma_f32 v6, v21, v6, -v7
	v_bfe_u32 v7, v6, 16, 1
	v_add3_u32 v6, v6, v7, s26
	global_store_short_d16_hi v[4:5], v6, off offset:192
.LBB0_734:
	s_or_b64 exec, exec, s[4:5]
	v_or_b32_e32 v4, 24, v216
	v_or_b32_e32 v5, s22, v4
	v_cmp_gt_i32_e32 vcc, s8, v5
	s_and_saveexec_b64 s[4:5], vcc
	s_cbranch_execz .LBB0_736
	v_lshlrev_b32_e32 v170, 12, v4
	v_lshl_add_u64 v[4:5], v[80:81], 0, v[170:171]
	global_load_ushort v6, v[4:5], off
	global_load_ushort v249, v[4:5], off offset:64
	global_load_ushort v250, v[4:5], off offset:128
	global_load_ushort v251, v[4:5], off offset:192
	s_waitcnt lgkmcnt(1)
	v_rcp_f32_e32 v0, v0
	s_waitcnt vmcnt(3)
	v_lshlrev_b32_e32 v6, 16, v6
	s_waitcnt lgkmcnt(0)
	v_mul_f32_e32 v6, v79, v6
	v_fma_f32 v6, v70, v0, -v6
	v_bfe_u32 v7, v6, 16, 1
	v_add3_u32 v6, v6, v7, s26
	global_store_short_d16_hi v[4:5], v6, off
	s_waitcnt vmcnt(3)
	v_mov_b32_e32 v6, v249
	v_lshlrev_b32_e32 v6, 16, v6
	v_mul_f32_e32 v6, v79, v6
	v_fma_f32 v6, v54, v0, -v6
	v_bfe_u32 v7, v6, 16, 1
	v_add3_u32 v6, v6, v7, s26
	global_store_short_d16_hi v[4:5], v6, off offset:64
	s_waitcnt vmcnt(3)
	v_mov_b32_e32 v6, v250
	v_lshlrev_b32_e32 v6, 16, v6
	v_mul_f32_e32 v6, v79, v6
	v_fma_f32 v6, v38, v0, -v6
	v_bfe_u32 v7, v6, 16, 1
	v_add3_u32 v6, v6, v7, s26
	global_store_short_d16_hi v[4:5], v6, off offset:128
	s_waitcnt vmcnt(3)
	v_mov_b32_e32 v6, v251
	v_lshlrev_b32_e32 v6, 16, v6
	v_mul_f32_e32 v6, v79, v6
	v_fma_f32 v0, v22, v0, -v6
	v_bfe_u32 v6, v0, 16, 1
	v_add3_u32 v0, v0, v6, s26
	global_store_short_d16_hi v[4:5], v0, off offset:192
.LBB0_736:
	s_or_b64 exec, exec, s[4:5]
	s_waitcnt lgkmcnt(1)
	v_or_b32_e32 v0, 25, v216
	v_or_b32_e32 v4, s22, v0
	v_cmp_gt_i32_e32 vcc, s8, v4
	s_and_saveexec_b64 s[4:5], vcc
	s_cbranch_execz .LBB0_738
	v_lshlrev_b32_e32 v170, 12, v0
	v_rcp_f32_e32 v4, v1
	v_lshl_add_u64 v[0:1], v[80:81], 0, v[170:171]
	global_load_ushort v5, v[0:1], off
	global_load_ushort v249, v[0:1], off offset:64
	global_load_ushort v250, v[0:1], off offset:128
	global_load_ushort v251, v[0:1], off offset:192
	s_waitcnt vmcnt(3)
	v_lshlrev_b32_e32 v5, 16, v5
	s_waitcnt lgkmcnt(0)
	v_mul_f32_e32 v5, v79, v5
	v_fma_f32 v5, v71, v4, -v5
	v_bfe_u32 v6, v5, 16, 1
	v_add3_u32 v5, v5, v6, s26
	global_store_short_d16_hi v[0:1], v5, off
	s_waitcnt vmcnt(3)
	v_mov_b32_e32 v5, v249
	v_lshlrev_b32_e32 v5, 16, v5
	v_mul_f32_e32 v5, v79, v5
	v_fma_f32 v5, v55, v4, -v5
	v_bfe_u32 v6, v5, 16, 1
	v_add3_u32 v5, v5, v6, s26
	global_store_short_d16_hi v[0:1], v5, off offset:64
	s_waitcnt vmcnt(3)
	v_mov_b32_e32 v5, v250
	v_lshlrev_b32_e32 v5, 16, v5
	v_mul_f32_e32 v5, v79, v5
	v_fma_f32 v5, v39, v4, -v5
	v_bfe_u32 v6, v5, 16, 1
	v_add3_u32 v5, v5, v6, s26
	global_store_short_d16_hi v[0:1], v5, off offset:128
	s_waitcnt vmcnt(3)
	v_mov_b32_e32 v5, v251
	v_lshlrev_b32_e32 v5, 16, v5
	v_mul_f32_e32 v5, v79, v5
	v_fma_f32 v4, v23, v4, -v5
	v_bfe_u32 v5, v4, 16, 1
	v_add3_u32 v4, v4, v5, s26
	global_store_short_d16_hi v[0:1], v4, off offset:192
.LBB0_738:
	s_or_b64 exec, exec, s[4:5]
	v_or_b32_e32 v0, 26, v216
	v_or_b32_e32 v1, s22, v0
	v_cmp_gt_i32_e32 vcc, s8, v1
	s_and_saveexec_b64 s[4:5], vcc
	s_cbranch_execz .LBB0_740
	v_lshlrev_b32_e32 v170, 12, v0
	v_lshl_add_u64 v[0:1], v[80:81], 0, v[170:171]
	global_load_ushort v4, v[0:1], off
	global_load_ushort v249, v[0:1], off offset:64
	global_load_ushort v250, v[0:1], off offset:128
	global_load_ushort v251, v[0:1], off offset:192
	v_rcp_f32_e32 v2, v2
	s_waitcnt vmcnt(3)
	v_lshlrev_b32_e32 v4, 16, v4
	s_waitcnt lgkmcnt(0)
	v_mul_f32_e32 v4, v79, v4
	v_fma_f32 v4, v72, v2, -v4
	v_bfe_u32 v5, v4, 16, 1
	v_add3_u32 v4, v4, v5, s26
	global_store_short_d16_hi v[0:1], v4, off
	s_waitcnt vmcnt(3)
	v_mov_b32_e32 v4, v249
	v_lshlrev_b32_e32 v4, 16, v4
	v_mul_f32_e32 v4, v79, v4
	v_fma_f32 v4, v56, v2, -v4
	v_bfe_u32 v5, v4, 16, 1
	v_add3_u32 v4, v4, v5, s26
	global_store_short_d16_hi v[0:1], v4, off offset:64
	s_waitcnt vmcnt(3)
	v_mov_b32_e32 v4, v250
	v_lshlrev_b32_e32 v4, 16, v4
	v_mul_f32_e32 v4, v79, v4
	v_fma_f32 v4, v40, v2, -v4
	v_bfe_u32 v5, v4, 16, 1
	v_add3_u32 v4, v4, v5, s26
	global_store_short_d16_hi v[0:1], v4, off offset:128
	s_waitcnt vmcnt(3)
	v_mov_b32_e32 v4, v251
	v_lshlrev_b32_e32 v4, 16, v4
	v_mul_f32_e32 v4, v79, v4
	v_fma_f32 v2, v24, v2, -v4
	v_bfe_u32 v4, v2, 16, 1
	v_add3_u32 v2, v2, v4, s26
	global_store_short_d16_hi v[0:1], v2, off offset:192

; #define SBAR() __builtin_amdgcn_sched_barrier(0)
; #define TILE_DQ(ti) (qposf - (float)TILE_KPOS(ti))
; #define TILE_SIDE(ti) (qlo - TILE_KPOS(ti) >= 63 ? 1 : (qhi - TILE_KPOS(ti) <= 0 ? -1 : 0))
; #define SLOAD(i, ti) do { const bf16* kp_ = TILE_K(ti); const bf16* vp_ = TILE_V(ti); \
;     sr_[i].vs0 = *(const ATT_GAS bf16x8*)(&vp_[(long)sr * LD + sc]); sr_[i].vs1 = *(const ATT_GAS bf16x8*)(&vp_[(long)(32 + sr) * LD + sc]); \
;     sr_[i].ks0 = *(const ATT_GAS bf16x8*)(&kp_[(long)sr * LD + sc]); sr_[i].ks1 = *(const ATT_GAS bf16x8*)(&kp_[(long)(32 + sr) * LD + sc]); } while (0)
; __device__ __forceinline__ void finishSM(f32x16& p0, f32x16& p1, float& l_reg, bf16x8& pa0, bf16x8& pa1, bf16x8& pa2, bf16x8& pa3) {
; #pragma unroll
;   for (int r = 0; r < 16; ++r) p0[r] = __builtin_amdgcn_exp2f(p0[r]);
; #pragma unroll
;   for (int r = 0; r < 16; ++r) p1[r] = __builtin_amdgcn_exp2f(p1[r]);
;   float ps = 0;
; #pragma unroll
;   for (int r = 0; r < 16; ++r) ps += p0[r];
; #pragma unroll
;   for (int r = 0; r < 16; ++r) ps += p1[r];
;   { auto rr = __builtin_amdgcn_permlane32_swap(__float_as_uint(ps), __float_as_uint(ps), false, false);
;     ps = __uint_as_float(rr[0]) + __uint_as_float(rr[1]); }
;   l_reg += ps;
;     ...
;   PK4(p0, 0, pa0); PK4(p0, 8, pa1); PK4(p1, 0, pa2); PK4(p1, 8, pa3);
; template <int J> ...
;     ...
;   for (int j = 1; j + 1 < NT; j += 2) {
;     SBAR(); qkt<0>(pB0, pB1, (bf16*)((char*)K_lds + SHM_K), qr, r32, hi, TILE_DQ(j), nsl, TILE_SIDE(j), mi);
;     finishSM(pA0, pA1, l_reg, pa0, pa1, pa2, pa3); SBAR();
;     SLOAD(SO, j + SDEPTH); SBAR();
.LBB0_757:
	v_readfirstlane_b32 s5, v248
	s_add_i32 s92, s20, s30
	s_add_i32 s10, s92, 1
	s_ashr_i32 s11, s10, 31
	s_lshl_b64 s[10:11], s[10:11], 18
	s_add_u32 s10, s89, s10
	s_addc_u32 s11, s24, s11
	s_add_i32 s93, s30, 1
	s_cmp_lt_i32 s93, s15
	s_cselect_b32 s10, s10, s16
	s_cselect_b32 s11, s11, s1
	s_ashr_i32 s93, s92, 31
	s_lshl_b64 s[92:93], s[92:93], 18
	s_add_u32 s92, s0, s92
	s_addc_u32 s93, s25, s93
	ds_read_b128 v[0:3], v229 offset:49152
	ds_read_b128 v[4:7], v229 offset:57344
	v_exp_f32_e32 v74, v74
	v_exp_f32_e32 v75, v75
	v_exp_f32_e32 v76, v76
	s_waitcnt lgkmcnt(1)
	v_mfma_f32_32x32x16_bf16 v[122:137], v[0:3], v[158:161], v[122:137]
	v_exp_f32_e32 v77, v77
	v_exp_f32_e32 v78, v78
	v_exp_f32_e32 v79, v79
	v_exp_f32_e32 v80, v80
	v_exp_f32_e32 v81, v81
	v_exp_f32_e32 v82, v82
	v_exp_f32_e32 v83, v83
	s_waitcnt lgkmcnt(0)
	v_mfma_f32_32x32x16_bf16 v[106:121], v[4:7], v[158:161], v[106:121]
	s_add_i32 m0, s5, 0x8000
	s_nop 0
	global_load_lds_dwordx4 v245, s[10:11]
	ds_read_b128 v[0:3], v230 offset:49152
	ds_read_b128 v[4:7], v230 offset:57344
	v_exp_f32_e32 v84, v84
	v_exp_f32_e32 v85, v85
	v_exp_f32_e32 v86, v86
	v_exp_f32_e32 v87, v87
	v_exp_f32_e32 v88, v88
	v_exp_f32_e32 v89, v89
	s_waitcnt lgkmcnt(1)
	v_mfma_f32_32x32x16_bf16 v[122:137], v[0:3], v[154:157], v[122:137]
	s_add_i32 s4, s30, 1
	s_waitcnt lgkmcnt(0)
	v_mfma_f32_32x32x16_bf16 v[106:121], v[4:7], v[154:157], v[106:121]
	ds_read_b128 v[0:3], v231 offset:49152
	ds_read_b128 v[4:7], v231 offset:57344
	s_waitcnt lgkmcnt(1)
	v_mfma_f32_32x32x16_bf16 v[122:137], v[0:3], v[150:153], v[122:137]
	s_waitcnt lgkmcnt(0)
	v_mfma_f32_32x32x16_bf16 v[106:121], v[4:7], v[150:153], v[106:121]
	s_add_i32 m0, s5, 0x8400
	s_nop 0
	global_load_lds_dwordx4 v246, s[10:11]
	ds_read_b128 v[0:3], v232 offset:49152
	ds_read_b128 v[4:7], v232 offset:57344
	s_waitcnt lgkmcnt(1)
	v_mfma_f32_32x32x16_bf16 v[122:137], v[0:3], v[146:149], v[122:137]
	s_waitcnt lgkmcnt(0)
	v_mfma_f32_32x32x16_bf16 v[106:121], v[4:7], v[146:149], v[106:121]
	ds_read_b128 v[0:3], v229 offset:49280
	ds_read_b128 v[4:7], v229 offset:57472
	s_waitcnt lgkmcnt(1)
	v_mfma_f32_32x32x16_bf16 v[122:137], v[0:3], v[142:145], v[122:137]
	s_waitcnt lgkmcnt(0)
	v_mfma_f32_32x32x16_bf16 v[106:121], v[4:7], v[142:145], v[106:121]
	s_add_i32 m0, s5, 0x4000
	s_nop 0
	global_load_lds_dwordx4 v247, s[92:93]
	ds_read_b128 v[0:3], v230 offset:49280
	ds_read_b128 v[4:7], v230 offset:57472
	s_waitcnt lgkmcnt(1)
	v_mfma_f32_32x32x16_bf16 v[122:137], v[0:3], v[138:141], v[122:137]
	s_waitcnt lgkmcnt(0)
	v_mfma_f32_32x32x16_bf16 v[106:121], v[4:7], v[138:141], v[106:121]
	ds_read_b128 v[0:3], v231 offset:49280
	ds_read_b128 v[4:7], v231 offset:57472
	s_waitcnt lgkmcnt(1)
	v_mfma_f32_32x32x16_bf16 v[122:137], v[0:3], v[166:169], v[122:137]
	s_waitcnt lgkmcnt(0)
	v_mfma_f32_32x32x16_bf16 v[106:121], v[4:7], v[166:169], v[106:121]
	s_add_i32 m0, s5, 0x4380
	s_nop 0
	global_load_lds_dwordx4 v247, s[92:93] offset:128
	ds_read_b128 v[0:3], v232 offset:49280
	ds_read_b128 v[4:7], v232 offset:57472
	s_waitcnt lgkmcnt(1)
	v_mfma_f32_32x32x16_bf16 v[122:137], v[0:3], v[162:165], v[122:137]
	v_exp_f32_e32 v0, v90
	v_exp_f32_e32 v1, v91
	v_exp_f32_e32 v2, v92
	v_exp_f32_e32 v3, v93
	v_exp_f32_e32 v90, v98
	v_add_f32_e32 v98, 0, v0
	v_add_f32_e32 v98, v1, v98
	s_waitcnt lgkmcnt(0)
	v_mfma_f32_32x32x16_bf16 v[106:121], v[4:7], v[162:165], v[106:121]
	v_exp_f32_e32 v4, v94
	v_exp_f32_e32 v5, v95
	v_exp_f32_e32 v6, v96
	v_add_f32_e32 v98, v2, v98
	v_exp_f32_e32 v7, v97
	v_add_f32_e32 v98, v3, v98
	v_add_f32_e32 v98, v4, v98
	v_exp_f32_e32 v91, v99
	v_add_f32_e32 v98, v5, v98
	v_exp_f32_e32 v92, v100
	v_add_f32_e32 v98, v6, v98
	v_exp_f32_e32 v93, v101
	v_add_f32_e32 v98, v7, v98
	v_exp_f32_e32 v94, v102
	v_add_f32_e32 v98, v90, v98
	v_exp_f32_e32 v95, v103
	v_add_f32_e32 v98, v91, v98
	v_exp_f32_e32 v96, v104
	v_add_f32_e32 v98, v92, v98
	v_exp_f32_e32 v97, v105
	v_add_f32_e32 v98, v93, v98
	v_add_f32_e32 v98, v94, v98
	v_add_f32_e32 v98, v95, v98
	v_add_f32_e32 v98, v96, v98
	v_add_f32_e32 v98, v97, v98
	v_add_f32_e32 v98, v74, v98
	v_add_f32_e32 v98, v75, v98
	v_add_f32_e32 v98, v76, v98
	v_add_f32_e32 v98, v77, v98
	v_add_f32_e32 v98, v78, v98
	v_add_f32_e32 v98, v79, v98
	v_add_f32_e32 v98, v80, v98
	v_add_f32_e32 v98, v81, v98
	v_add_f32_e32 v98, v82, v98
	v_add_f32_e32 v98, v83, v98
	v_add_f32_e32 v98, v84, v98
	v_add_f32_e32 v98, v85, v98
	v_add_f32_e32 v98, v86, v98
	v_add_f32_e32 v98, v87, v98
	v_add_f32_e32 v98, v88, v98
	v_add_f32_e32 v233, v89, v98
	v_mov_b32_e32 v234, v233
	v_cvt_pk_bf16_f32 v0, v0, v1
	v_cvt_pk_bf16_f32 v1, v2, v3
	v_cvt_pk_bf16_f32 v2, v4, v5
	v_cvt_pk_bf16_f32 v3, v6, v7
	v_cvt_pk_bf16_f32 v4, v90, v91
	v_cvt_pk_bf16_f32 v5, v92, v93
	v_cvt_pk_bf16_f32 v6, v94, v95
	v_cvt_pk_bf16_f32 v7, v96, v97
	v_cvt_pk_bf16_f32 v74, v74, v75
	v_cvt_pk_bf16_f32 v75, v76, v77
	v_cvt_pk_bf16_f32 v76, v78, v79
	v_cvt_pk_bf16_f32 v77, v80, v81
	v_cvt_pk_bf16_f32 v78, v82, v83
	v_cvt_pk_bf16_f32 v79, v84, v85
	v_cvt_pk_bf16_f32 v80, v86, v87
	v_cvt_pk_bf16_f32 v81, v88, v89
	s_nop 1
	v_permlane32_swap_b32_e32 v233, v234
	v_permlane32_swap_b32_e32 v0, v2
	v_permlane32_swap_b32_e32 v74, v76
	v_permlane32_swap_b32_e32 v75, v77
	v_permlane32_swap_b32_e32 v78, v80
	v_permlane32_swap_b32_e32 v79, v81
	v_permlane32_swap_b32_e32 v1, v3
	v_permlane32_swap_b32_e32 v4, v6
	v_permlane32_swap_b32_e32 v5, v7
	s_add_i32 s3, s20, s30
	s_add_i32 s10, s3, 1
	s_ashr_i32 s11, s10, 31
	s_lshl_b64 s[10:11], s[10:11], 18
	s_add_u32 s9, s89, s10
	s_addc_u32 s31, s24, s11
	s_add_u32 s10, s0, s10
	s_addc_u32 s11, s25, s11
	s_cmp_lt_i32 s4, s15
	s_cselect_b64 vcc, -1, 0
	s_and_b64 s[4:5], vcc, exec
	s_cselect_b32 s5, s31, s1
	s_cselect_b32 s4, s9, s16
	s_cselect_b32 s11, s11, s29
	s_cselect_b32 s10, s10, s28
	s_waitcnt lgkmcnt(0)
; #define PV_WAIT4() do { asm volatile("s_waitcnt lgkmcnt(4)" ::: "memory"); SBAR(); } while (0)
; #define PV_WAIT0() do { asm volatile("s_waitcnt lgkmcnt(0)" ::: "memory"); SBAR(); } while (0)
; #define PV_MM(od, pX, pY, g) do { od = __builtin_amdgcn_mfma_f32_32x32x16_bf16(pX, PK(g.l0, g.h0), od, 0, 0, 0); od = __builtin_amdgcn_mfma_f32_32x32x16_bf16(pY, PK(g.l1, g.h1), od, 0, 0, 0); } while (0)
; template <int MODE>
; __device__ __forceinline__ void qkt(f32x16& p0, f32x16& p1, const bf16* Ks, const bf16x8* qr, int r32, int hi, float dq, float nsl, int side, float mi) {
;   if (MODE == 0) {
;     if (side != 0) {
;       const float sg = side > 0 ? -nsl : nsl, bb = -sg * dq - mi;
; #pragma unroll
;       for (int r = 0; r < 16; ++r) { const float c = (float)((r & 3) + 8 * (r >> 2)); p0[r] = fmaf(c, sg, bb); p1[r] = fmaf(c + 32.f, sg, bb); }
;     } else {
; #pragma unroll
;       for (int r = 0; r < 16; ++r) { const float c = (float)((r & 3) + 8 * (r >> 2)); p0[r] = fmaf(fabsf(dq - c), nsl, -mi); p1[r] = fmaf(fabsf(dq - (c + 32.f)), nsl, -mi); }
;     }
; __device__ __forceinline__ void pv_d0(f32x16* o, int vb, bf16x8 pa0, bf16x8 pa1, bf16x8 pa2, bf16x8 pa3) {
;   asm volatile("s_waitcnt lgkmcnt(0)" ::: "memory");
;   VG a0 = pv_reads<0, 0>(vb), b0 = pv_reads<0, 2>(vb);
;   PV_WAIT4(); PV_MM(o[0], pa0, pa1, a0); VG a1 = pv_reads<1, 0>(vb);
;   PV_WAIT4(); PV_MM(o[0], pa2, pa3, b0); VG b1 = pv_reads<1, 2>(vb);
;   PV_WAIT4(); PV_MM(o[1], pa0, pa1, a1); VG a2 = pv_reads<2, 0>(vb);
;   PV_WAIT4(); PV_MM(o[1], pa2, pa3, b1); VG b2 = pv_reads<2, 2>(vb);
;   PV_WAIT4(); PV_MM(o[2], pa0, pa1, a2); VG a3 = pv_reads<3, 0>(vb);
;   PV_WAIT4(); PV_MM(o[2], pa2, pa3, b2); VG b3 = pv_reads<3, 2>(vb);
;   PV_WAIT4(); PV_MM(o[3], pa0, pa1, a3);
;   PV_WAIT0(); PV_MM(o[3], pa2, pa3, b3);
; }
	ds_read_b64_tr_b16 v[98:99], v219 offset:0
	ds_read_b64_tr_b16 v[100:101], v219 offset:0x800
	ds_read_b64_tr_b16 v[102:103], v219 offset:0x1000
	ds_read_b64_tr_b16 v[104:105], v219 offset:0x1800
	ds_read_b64_tr_b16 v[236:237], v219 offset:0x2000
	ds_read_b64_tr_b16 v[238:239], v219 offset:0x2800
	ds_read_b64_tr_b16 v[240:241], v219 offset:0x3000
	ds_read_b64_tr_b16 v[242:243], v219 offset:0x3800
	s_waitcnt lgkmcnt(4)
	s_nop 0
	v_mfma_f32_32x32x16_bf16 v[58:73], v[0:3], v[98:101], v[58:73]
	ds_read_b64_tr_b16 v[98:99], v219 offset:0x200
	ds_read_b64_tr_b16 v[100:101], v219 offset:0xa00
	v_mfma_f32_32x32x16_bf16 v[58:73], v[4:7], v[102:105], v[58:73]
	ds_read_b64_tr_b16 v[102:103], v219 offset:0x1200
	ds_read_b64_tr_b16 v[104:105], v219 offset:0x1a00
	s_waitcnt lgkmcnt(4)
	v_mfma_f32_32x32x16_bf16 v[58:73], v[74:77], v[236:239], v[58:73]
	ds_read_b64_tr_b16 v[236:237], v219 offset:0x2200
	ds_read_b64_tr_b16 v[238:239], v219 offset:0x2a00
	v_mfma_f32_32x32x16_bf16 v[58:73], v[78:81], v[240:243], v[58:73]
	ds_read_b64_tr_b16 v[240:241], v219 offset:0x3200
	ds_read_b64_tr_b16 v[242:243], v219 offset:0x3a00
	s_waitcnt lgkmcnt(4)
	v_mfma_f32_32x32x16_bf16 v[42:57], v[0:3], v[98:101], v[42:57]
	ds_read_b64_tr_b16 v[98:99], v219 offset:0x400
	ds_read_b64_tr_b16 v[100:101], v219 offset:0xc00
	v_mfma_f32_32x32x16_bf16 v[42:57], v[4:7], v[102:105], v[42:57]
	ds_read_b64_tr_b16 v[102:103], v219 offset:0x1400
	ds_read_b64_tr_b16 v[104:105], v219 offset:0x1c00
	s_waitcnt lgkmcnt(4)
	v_mfma_f32_32x32x16_bf16 v[42:57], v[74:77], v[236:239], v[42:57]
	ds_read_b64_tr_b16 v[236:237], v219 offset:0x2400
	ds_read_b64_tr_b16 v[238:239], v219 offset:0x2c00
	v_mfma_f32_32x32x16_bf16 v[42:57], v[78:81], v[240:243], v[42:57]
	ds_read_b64_tr_b16 v[240:241], v219 offset:0x3400
	ds_read_b64_tr_b16 v[242:243], v219 offset:0x3c00
	s_waitcnt lgkmcnt(4)
	v_mfma_f32_32x32x16_bf16 v[26:41], v[0:3], v[98:101], v[26:41]
	ds_read_b64_tr_b16 v[98:99], v219 offset:0x600
	ds_read_b64_tr_b16 v[100:101], v219 offset:0xe00
	v_mfma_f32_32x32x16_bf16 v[26:41], v[4:7], v[102:105], v[26:41]
	ds_read_b64_tr_b16 v[102:103], v219 offset:0x1600
	ds_read_b64_tr_b16 v[104:105], v219 offset:0x1e00
	s_waitcnt lgkmcnt(4)
	v_mfma_f32_32x32x16_bf16 v[26:41], v[74:77], v[236:239], v[26:41]
	ds_read_b64_tr_b16 v[236:237], v219 offset:0x2600
	ds_read_b64_tr_b16 v[238:239], v219 offset:0x2e00
	v_mfma_f32_32x32x16_bf16 v[26:41], v[78:81], v[240:243], v[26:41]
	ds_read_b64_tr_b16 v[240:241], v219 offset:0x3600
	ds_read_b64_tr_b16 v[242:243], v219 offset:0x3e00
	s_waitcnt lgkmcnt(4)
	v_mfma_f32_32x32x16_bf16 v[10:25], v[0:3], v[98:101], v[10:25]
	s_waitcnt lgkmcnt(0)
	v_mfma_f32_32x32x16_bf16 v[10:25], v[4:7], v[102:105], v[10:25]
	v_mfma_f32_32x32x16_bf16 v[10:25], v[74:77], v[236:239], v[10:25]
	v_mfma_f32_32x32x16_bf16 v[10:25], v[78:81], v[240:243], v[10:25]
	s_cselect_b32 s4, s21, 0x10000000
	s_add_i32 s5, s4, s12
	v_cvt_f32_i32_e32 v0, s27
	s_cmp_lt_i32 s5, 63
	s_cselect_b64 s[10:11], -1, 0
	s_add_i32 s4, s4, s13
	s_cmp_gt_i32 s4, 0
	s_cselect_b64 s[4:5], -1, 0
	v_cndmask_b32_e32 v0, v214, v0, vcc
	s_and_b64 s[4:5], s[10:11], s[4:5]
	v_sub_f32_e32 v0, v176, v0
	s_andn2_b64 vcc, exec, s[4:5]
	s_mov_b64 s[4:5], -1
	s_cbranch_vccz .LBB0_759
	v_cndmask_b32_e64 v2, -v172, v172, s[10:11]
	v_fma_f32 v4, v0, -v2, -v174
	v_fma_f32 v90, 0, v2, v4
	v_add_f32_e32 v91, v2, v4
	v_pk_fma_f32 v[74:75], v[2:3], s[34:35], v[4:5] op_sel_hi:[0,1,0]
	v_pk_fma_f32 v[92:93], v[2:3], s[36:37], v[4:5] op_sel_hi:[0,1,0]
	v_pk_fma_f32 v[76:77], v[2:3], s[38:39], v[4:5] op_sel_hi:[0,1,0]
	v_pk_fma_f32 v[94:95], v[2:3], s[40:41], v[4:5] op_sel_hi:[0,1,0]
	v_pk_fma_f32 v[78:79], v[2:3], s[42:43], v[4:5] op_sel_hi:[0,1,0]
	v_pk_fma_f32 v[96:97], v[2:3], s[44:45], v[4:5] op_sel_hi:[0,1,0]
	v_pk_fma_f32 v[80:81], v[2:3], s[46:47], v[4:5] op_sel_hi:[0,1,0]
	v_pk_fma_f32 v[98:99], v[2:3], s[48:49], v[4:5] op_sel_hi:[0,1,0]
	v_pk_fma_f32 v[82:83], v[2:3], s[50:51], v[4:5] op_sel_hi:[0,1,0]
	v_pk_fma_f32 v[100:101], v[2:3], s[52:53], v[4:5] op_sel_hi:[0,1,0]
	v_pk_fma_f32 v[84:85], v[2:3], s[54:55], v[4:5] op_sel_hi:[0,1,0]
	v_pk_fma_f32 v[102:103], v[2:3], s[56:57], v[4:5] op_sel_hi:[0,1,0]
	v_pk_fma_f32 v[86:87], v[2:3], s[58:59], v[4:5] op_sel_hi:[0,1,0]
	v_fmamk_f32 v88, v2, 0x42680000, v4
	v_pk_fma_f32 v[104:105], v[2:3], s[60:61], v[4:5] op_sel_hi:[0,1,0]
	v_fmac_f32_e32 v4, 0x426c0000, v2
	s_mov_b64 s[4:5], 0
	v_mov_b32_e32 v89, v4

; #define SBAR() __builtin_amdgcn_sched_barrier(0)
; #define TILE_DQ(ti) (qposf - (float)TILE_KPOS(ti))
; #define TILE_SIDE(ti) (qlo - TILE_KPOS(ti) >= 63 ? 1 : (qhi - TILE_KPOS(ti) <= 0 ? -1 : 0))
; #define SLOAD(i, ti) do { const bf16* kp_ = TILE_K(ti); const bf16* vp_ = TILE_V(ti); \
;     sr_[i].vs0 = *(const ATT_GAS bf16x8*)(&vp_[(long)sr * LD + sc]); sr_[i].vs1 = *(const ATT_GAS bf16x8*)(&vp_[(long)(32 + sr) * LD + sc]); \
;     sr_[i].ks0 = *(const ATT_GAS bf16x8*)(&kp_[(long)sr * LD + sc]); sr_[i].ks1 = *(const ATT_GAS bf16x8*)(&kp_[(long)(32 + sr) * LD + sc]); } while (0)
; #define SWRITE(b, i) do { *(bf16x8*)((char*)V_lds + (b) * SHM_V + vst0) = sr_[i].vs0;          \
;     *(bf16x8*)((char*)V_lds + (b) * SHM_V + vst1) = sr_[i].vs1; int kc = sc * 2;               \
;     *(bf16x8*)((char*)K_lds + (b) * SHM_K + KSWZ(sr, kc)) = sr_[i].ks0;                       \
;     *(bf16x8*)((char*)K_lds + (b) * SHM_K + KSWZ(32 + sr, kc)) = sr_[i].ks1; } while (0)
; #define SWAIT() do { if constexpr (SDEPTH == 2) asm volatile("s_waitcnt vmcnt(4)" ::: "memory"); else asm volatile("s_waitcnt vmcnt(0)" ::: "memory"); } while (0)
; __device__ __forceinline__ void finishSM(f32x16& p0, f32x16& p1, float& l_reg, bf16x8& pa0, bf16x8& pa1, bf16x8& pa2, bf16x8& pa3) {
; #pragma unroll
;   for (int r = 0; r < 16; ++r) p0[r] = __builtin_amdgcn_exp2f(p0[r]);
; #pragma unroll
;   for (int r = 0; r < 16; ++r) p1[r] = __builtin_amdgcn_exp2f(p1[r]);
;   float ps = 0;
; #pragma unroll
;   for (int r = 0; r < 16; ++r) ps += p0[r];
; #pragma unroll
;   for (int r = 0; r < 16; ++r) ps += p1[r];
;   { auto rr = __builtin_amdgcn_permlane32_swap(__float_as_uint(ps), __float_as_uint(ps), false, false);
;     ps = __uint_as_float(rr[0]) + __uint_as_float(rr[1]); }
;   l_reg += ps;
;     ...
;   PK4(p0, 0, pa0); PK4(p0, 8, pa1); PK4(p1, 0, pa2); PK4(p1, 8, pa3);
; template <int J> ...
;     ...
;     __syncthreads(); SWAIT(); SWRITE(0, SE);
;     __syncthreads();
;     SBAR(); qkt<0>(pA0, pA1, K_lds, qr, r32, hi, TILE_DQ(j + 1), nsl, TILE_SIDE(j + 1), mi);
;     finishSM(pB0, pB1, l_reg, pa0, pa1, pa2, pa3); SBAR();
;     if (SDEPTH == 1 || j + 3 < NT) SLOAD(SE, j + 1 + SDEPTH); SBAR();
.LBB0_761:
	s_waitcnt vmcnt(0)
	s_barrier
	v_readfirstlane_b32 s5, v248
	s_add_i32 s92, s20, s30
	s_add_i32 s10, s92, 2
	s_ashr_i32 s11, s10, 31
	s_lshl_b64 s[10:11], s[10:11], 18
	s_add_u32 s10, s89, s10
	s_addc_u32 s11, s24, s11
	s_add_i32 s93, s30, 2
	s_cmp_lt_i32 s93, s15
	s_cselect_b32 s10, s10, s16
	s_cselect_b32 s11, s11, s1
	s_add_i32 s92, s92, 1
	s_ashr_i32 s93, s92, 31
	s_lshl_b64 s[92:93], s[92:93], 18
	s_add_u32 s92, s0, s92
	s_addc_u32 s93, s25, s93
	v_add_f32_e32 v0, v233, v234
	v_add_f32_e32 v173, v226, v0
	ds_read_b128 v[0:3], v229 offset:32768
	ds_read_b128 v[4:7], v229 offset:40960
	v_exp_f32_e32 v106, v106
	v_exp_f32_e32 v107, v107
	s_waitcnt lgkmcnt(1)
	v_mfma_f32_32x32x16_bf16 v[90:105], v[0:3], v[158:161], v[90:105]
	v_exp_f32_e32 v108, v108
	v_exp_f32_e32 v109, v109
	v_exp_f32_e32 v110, v110
	v_exp_f32_e32 v111, v111
	v_exp_f32_e32 v112, v112
	v_exp_f32_e32 v113, v113
	v_exp_f32_e32 v114, v114
	s_waitcnt lgkmcnt(0)
	v_mfma_f32_32x32x16_bf16 v[74:89], v[4:7], v[158:161], v[74:89]
	s_add_i32 m0, s5, 0xc000
	s_nop 0
	global_load_lds_dwordx4 v245, s[10:11]
	ds_read_b128 v[0:3], v230 offset:32768
	ds_read_b128 v[4:7], v230 offset:40960
	v_exp_f32_e32 v115, v115
	v_exp_f32_e32 v116, v116
	v_exp_f32_e32 v117, v117
	v_exp_f32_e32 v118, v118
	v_exp_f32_e32 v119, v119
	v_exp_f32_e32 v120, v120
	s_waitcnt lgkmcnt(1)
	v_mfma_f32_32x32x16_bf16 v[90:105], v[0:3], v[154:157], v[90:105]
	v_exp_f32_e32 v121, v121
	s_waitcnt lgkmcnt(0)
	v_mfma_f32_32x32x16_bf16 v[74:89], v[4:7], v[154:157], v[74:89]
	ds_read_b128 v[0:3], v231 offset:32768
	ds_read_b128 v[4:7], v231 offset:40960
	s_waitcnt lgkmcnt(1)
	v_mfma_f32_32x32x16_bf16 v[90:105], v[0:3], v[150:153], v[90:105]
	s_waitcnt lgkmcnt(0)
	v_mfma_f32_32x32x16_bf16 v[74:89], v[4:7], v[150:153], v[74:89]
	s_add_i32 m0, s5, 0xc400
	s_nop 0
	global_load_lds_dwordx4 v246, s[10:11]
	ds_read_b128 v[0:3], v232 offset:32768
	ds_read_b128 v[4:7], v232 offset:40960
	s_waitcnt lgkmcnt(1)
	v_mfma_f32_32x32x16_bf16 v[90:105], v[0:3], v[146:149], v[90:105]
	s_waitcnt lgkmcnt(0)
	v_mfma_f32_32x32x16_bf16 v[74:89], v[4:7], v[146:149], v[74:89]
	ds_read_b128 v[0:3], v229 offset:32896
	ds_read_b128 v[4:7], v229 offset:41088
	s_waitcnt lgkmcnt(1)
	v_mfma_f32_32x32x16_bf16 v[90:105], v[0:3], v[142:145], v[90:105]
	s_waitcnt lgkmcnt(0)
	v_mfma_f32_32x32x16_bf16 v[74:89], v[4:7], v[142:145], v[74:89]
	s_add_i32 m0, s5, 0x0
	s_nop 0
	global_load_lds_dwordx4 v247, s[92:93]
	ds_read_b128 v[0:3], v230 offset:32896
	ds_read_b128 v[4:7], v230 offset:41088
	s_waitcnt lgkmcnt(1)
	v_mfma_f32_32x32x16_bf16 v[90:105], v[0:3], v[138:141], v[90:105]
	s_waitcnt lgkmcnt(0)
	v_mfma_f32_32x32x16_bf16 v[74:89], v[4:7], v[138:141], v[74:89]
	ds_read_b128 v[0:3], v231 offset:32896
	ds_read_b128 v[4:7], v231 offset:41088
	s_waitcnt lgkmcnt(1)
	v_mfma_f32_32x32x16_bf16 v[90:105], v[0:3], v[166:169], v[90:105]
	s_waitcnt lgkmcnt(0)
	v_mfma_f32_32x32x16_bf16 v[74:89], v[4:7], v[166:169], v[74:89]
	s_add_i32 m0, s5, 0x380
	s_nop 0
	global_load_lds_dwordx4 v247, s[92:93] offset:128
	ds_read_b128 v[0:3], v232 offset:32896
	ds_read_b128 v[4:7], v232 offset:41088
	s_waitcnt lgkmcnt(1)
	v_mfma_f32_32x32x16_bf16 v[90:105], v[0:3], v[162:165], v[90:105]
	v_exp_f32_e32 v0, v122
	v_exp_f32_e32 v1, v123
	v_exp_f32_e32 v2, v124
	v_exp_f32_e32 v3, v125
	v_exp_f32_e32 v122, v130
	v_add_f32_e32 v130, 0, v0
	v_add_f32_e32 v130, v1, v130
	s_waitcnt lgkmcnt(0)
	v_mfma_f32_32x32x16_bf16 v[74:89], v[4:7], v[162:165], v[74:89]
	v_exp_f32_e32 v4, v126
	v_exp_f32_e32 v5, v127
	v_exp_f32_e32 v6, v128
	v_add_f32_e32 v130, v2, v130
	v_exp_f32_e32 v7, v129
	v_add_f32_e32 v130, v3, v130
	v_add_f32_e32 v130, v4, v130
	v_exp_f32_e32 v123, v131
	v_add_f32_e32 v130, v5, v130
	v_exp_f32_e32 v124, v132
	v_add_f32_e32 v130, v6, v130
	v_exp_f32_e32 v125, v133
	v_add_f32_e32 v130, v7, v130
	v_exp_f32_e32 v126, v134
	v_add_f32_e32 v130, v122, v130
	v_exp_f32_e32 v127, v135
	v_add_f32_e32 v130, v123, v130
	v_exp_f32_e32 v128, v136
	v_add_f32_e32 v130, v124, v130
	v_exp_f32_e32 v129, v137
	v_add_f32_e32 v130, v125, v130
	v_add_f32_e32 v130, v126, v130
	v_add_f32_e32 v130, v127, v130
	v_add_f32_e32 v130, v128, v130
	v_add_f32_e32 v130, v129, v130
	v_add_f32_e32 v130, v106, v130
	v_add_f32_e32 v130, v107, v130
	v_add_f32_e32 v130, v108, v130
	v_add_f32_e32 v130, v109, v130
	v_add_f32_e32 v130, v110, v130
	v_add_f32_e32 v130, v111, v130
	v_add_f32_e32 v130, v112, v130
	v_add_f32_e32 v130, v113, v130
	v_add_f32_e32 v130, v114, v130
	v_add_f32_e32 v130, v115, v130
	v_add_f32_e32 v130, v116, v130
	v_add_f32_e32 v130, v117, v130
	v_add_f32_e32 v130, v118, v130
	v_add_f32_e32 v130, v119, v130
	v_add_f32_e32 v130, v120, v130
	v_add_f32_e32 v130, v121, v130
	v_mov_b32_e32 v131, v130
	s_nop 1
	v_permlane32_swap_b32_e32 v130, v131
	v_add_f32_e32 v130, v130, v131
	v_add_f32_e32 v226, v173, v130
	v_cvt_pk_bf16_f32 v0, v0, v1
	v_cvt_pk_bf16_f32 v1, v2, v3
	v_cvt_pk_bf16_f32 v2, v4, v5
	v_cvt_pk_bf16_f32 v3, v6, v7
	v_cvt_pk_bf16_f32 v4, v122, v123
	v_cvt_pk_bf16_f32 v5, v124, v125
	v_cvt_pk_bf16_f32 v6, v126, v127
	v_cvt_pk_bf16_f32 v7, v128, v129
	v_cvt_pk_bf16_f32 v106, v106, v107
	v_cvt_pk_bf16_f32 v107, v108, v109
	v_cvt_pk_bf16_f32 v108, v110, v111
	v_cvt_pk_bf16_f32 v109, v112, v113
	v_cvt_pk_bf16_f32 v110, v114, v115
	v_cvt_pk_bf16_f32 v111, v116, v117
	v_cvt_pk_bf16_f32 v112, v118, v119
	v_cvt_pk_bf16_f32 v113, v120, v121
	s_nop 0
	v_permlane32_swap_b32_e32 v0, v2
	v_permlane32_swap_b32_e32 v1, v3
	v_permlane32_swap_b32_e32 v4, v6
	v_permlane32_swap_b32_e32 v5, v7
	v_permlane32_swap_b32_e32 v106, v108
	v_permlane32_swap_b32_e32 v107, v109
	v_permlane32_swap_b32_e32 v110, v112
	v_permlane32_swap_b32_e32 v111, v113
	s_add_i32 s10, s3, 2
	s_ashr_i32 s11, s10, 31
	s_add_i32 s4, s30, 2
	s_lshl_b64 s[10:11], s[10:11], 18
	s_add_u32 s3, s89, s10
	s_addc_u32 s5, s24, s11
	s_add_u32 s9, s0, s10
	s_addc_u32 s31, s25, s11
	s_cmp_lt_i32 s4, s15
	s_cselect_b32 s11, s5, s1
	s_cselect_b32 s10, s3, s16
	s_cselect_b32 s93, s31, s29
	s_cselect_b32 s92, s9, s28
	s_waitcnt lgkmcnt(0)
; #define PV_WAIT4() do { asm volatile("s_waitcnt lgkmcnt(4)" ::: "memory"); SBAR(); } while (0)
; #define PV_WAIT0() do { asm volatile("s_waitcnt lgkmcnt(0)" ::: "memory"); SBAR(); } while (0)
; #define PV_MM(od, pX, pY, g) do { od = __builtin_amdgcn_mfma_f32_32x32x16_bf16(pX, PK(g.l0, g.h0), od, 0, 0, 0); od = __builtin_amdgcn_mfma_f32_32x32x16_bf16(pY, PK(g.l1, g.h1), od, 0, 0, 0); } while (0)
; template <int MODE>
; __device__ __forceinline__ void qkt(f32x16& p0, f32x16& p1, const bf16* Ks, const bf16x8* qr, int r32, int hi, float dq, float nsl, int side, float mi) {
;   if (MODE == 0) {
;     if (side != 0) {
;       const float sg = side > 0 ? -nsl : nsl, bb = -sg * dq - mi;
; #pragma unroll
;       for (int r = 0; r < 16; ++r) { const float c = (float)((r & 3) + 8 * (r >> 2)); p0[r] = fmaf(c, sg, bb); p1[r] = fmaf(c + 32.f, sg, bb); }
;     } else {
; #pragma unroll
;       for (int r = 0; r < 16; ++r) { const float c = (float)((r & 3) + 8 * (r >> 2)); p0[r] = fmaf(fabsf(dq - c), nsl, -mi); p1[r] = fmaf(fabsf(dq - (c + 32.f)), nsl, -mi); }
;     }
; __device__ __forceinline__ void pv_d0(f32x16* o, int vb, bf16x8 pa0, bf16x8 pa1, bf16x8 pa2, bf16x8 pa3) {
;   asm volatile("s_waitcnt lgkmcnt(0)" ::: "memory");
;   VG a0 = pv_reads<0, 0>(vb), b0 = pv_reads<0, 2>(vb);
;   PV_WAIT4(); PV_MM(o[0], pa0, pa1, a0); VG a1 = pv_reads<1, 0>(vb);
;   PV_WAIT4(); PV_MM(o[0], pa2, pa3, b0); VG b1 = pv_reads<1, 2>(vb);
;   PV_WAIT4(); PV_MM(o[1], pa0, pa1, a1); VG a2 = pv_reads<2, 0>(vb);
;   PV_WAIT4(); PV_MM(o[1], pa2, pa3, b1); VG b2 = pv_reads<2, 2>(vb);
;   PV_WAIT4(); PV_MM(o[2], pa0, pa1, a2); VG a3 = pv_reads<3, 0>(vb);
;   PV_WAIT4(); PV_MM(o[2], pa2, pa3, b2); VG b3 = pv_reads<3, 2>(vb);
;   PV_WAIT4(); PV_MM(o[3], pa0, pa1, a3);
;   PV_WAIT0(); PV_MM(o[3], pa2, pa3, b3);
; }
	ds_read_b64_tr_b16 v[130:131], v228 offset:0
	ds_read_b64_tr_b16 v[132:133], v228 offset:0x800
	ds_read_b64_tr_b16 v[134:135], v228 offset:0x1000
	ds_read_b64_tr_b16 v[136:137], v228 offset:0x1800
	ds_read_b64_tr_b16 v[234:235], v228 offset:0x2000
	ds_read_b64_tr_b16 v[236:237], v228 offset:0x2800
	ds_read_b64_tr_b16 v[238:239], v228 offset:0x3000
	ds_read_b64_tr_b16 v[240:241], v228 offset:0x3800
	s_waitcnt lgkmcnt(4)
	s_nop 0
	v_mfma_f32_32x32x16_bf16 v[58:73], v[0:3], v[130:133], v[58:73]
	ds_read_b64_tr_b16 v[130:131], v228 offset:0x200
	ds_read_b64_tr_b16 v[132:133], v228 offset:0xa00
	v_mfma_f32_32x32x16_bf16 v[58:73], v[4:7], v[134:137], v[58:73]
	ds_read_b64_tr_b16 v[134:135], v228 offset:0x1200
	ds_read_b64_tr_b16 v[136:137], v228 offset:0x1a00
	s_waitcnt lgkmcnt(4)
	v_mfma_f32_32x32x16_bf16 v[58:73], v[106:109], v[234:237], v[58:73]
	ds_read_b64_tr_b16 v[234:235], v228 offset:0x2200
	ds_read_b64_tr_b16 v[236:237], v228 offset:0x2a00
	v_mfma_f32_32x32x16_bf16 v[58:73], v[110:113], v[238:241], v[58:73]
	ds_read_b64_tr_b16 v[238:239], v228 offset:0x3200
	ds_read_b64_tr_b16 v[240:241], v228 offset:0x3a00
	s_waitcnt lgkmcnt(4)
	v_mfma_f32_32x32x16_bf16 v[42:57], v[0:3], v[130:133], v[42:57]
	ds_read_b64_tr_b16 v[130:131], v228 offset:0x400
	ds_read_b64_tr_b16 v[132:133], v228 offset:0xc00
	v_mfma_f32_32x32x16_bf16 v[42:57], v[4:7], v[134:137], v[42:57]
	ds_read_b64_tr_b16 v[134:135], v228 offset:0x1400
	ds_read_b64_tr_b16 v[136:137], v228 offset:0x1c00
	s_waitcnt lgkmcnt(4)
	v_mfma_f32_32x32x16_bf16 v[42:57], v[106:109], v[234:237], v[42:57]
	ds_read_b64_tr_b16 v[234:235], v228 offset:0x2400
	ds_read_b64_tr_b16 v[236:237], v228 offset:0x2c00
	v_mfma_f32_32x32x16_bf16 v[42:57], v[110:113], v[238:241], v[42:57]
	ds_read_b64_tr_b16 v[238:239], v228 offset:0x3400
	ds_read_b64_tr_b16 v[240:241], v228 offset:0x3c00
	s_waitcnt lgkmcnt(4)
	v_mfma_f32_32x32x16_bf16 v[26:41], v[0:3], v[130:133], v[26:41]
	ds_read_b64_tr_b16 v[130:131], v228 offset:0x600
	ds_read_b64_tr_b16 v[132:133], v228 offset:0xe00
	v_mfma_f32_32x32x16_bf16 v[26:41], v[4:7], v[134:137], v[26:41]
	ds_read_b64_tr_b16 v[134:135], v228 offset:0x1600
	ds_read_b64_tr_b16 v[136:137], v228 offset:0x1e00
	s_waitcnt lgkmcnt(4)
	v_mfma_f32_32x32x16_bf16 v[26:41], v[106:109], v[234:237], v[26:41]
	ds_read_b64_tr_b16 v[234:235], v228 offset:0x2600
	ds_read_b64_tr_b16 v[236:237], v228 offset:0x2e00
	v_mfma_f32_32x32x16_bf16 v[26:41], v[110:113], v[238:241], v[26:41]
	ds_read_b64_tr_b16 v[238:239], v228 offset:0x3600
	ds_read_b64_tr_b16 v[240:241], v228 offset:0x3e00
	s_waitcnt lgkmcnt(4)
	v_mfma_f32_32x32x16_bf16 v[10:25], v[0:3], v[130:133], v[10:25]
	s_waitcnt lgkmcnt(0)
	v_mfma_f32_32x32x16_bf16 v[10:25], v[4:7], v[134:137], v[10:25]
	v_mfma_f32_32x32x16_bf16 v[10:25], v[106:109], v[234:237], v[10:25]
	v_mfma_f32_32x32x16_bf16 v[10:25], v[110:113], v[238:241], v[10:25]
	s_addk_i32 s21, 0xff80
	s_addk_i32 s27, 0x80
	s_add_i32 s3, s30, 3
	s_cmp_ge_i32 s3, s14
	s_cbranch_scc1 .Lmy_i2_exit0
	s_mov_b32 s30, s4
	s_sub_i32 s3, s27, 64
	v_cvt_f32_i32_e32 v0, s3
	s_add_i32 s3, s21, 64
	s_cmp_lt_i32 s30, s15
	s_cselect_b64 vcc, -1, 0
	s_and_b64 s[4:5], vcc, exec
	s_cselect_b32 s3, s3, 0x10000000
	s_add_i32 s4, s3, s12
	s_cmp_lt_i32 s4, 63
	s_cselect_b64 s[10:11], -1, 0
	s_add_i32 s3, s3, s13
	s_cmp_gt_i32 s3, 0
	s_cselect_b64 s[4:5], -1, 0
	v_cndmask_b32_e32 v0, v214, v0, vcc
	s_and_b64 s[4:5], s[10:11], s[4:5]
	v_sub_f32_e32 v0, v176, v0
	s_andn2_b64 vcc, exec, s[4:5]
	s_mov_b64 s[4:5], -1
	s_cbranch_vccz .Lmy_i2_ha
	v_cndmask_b32_e64 v2, -v172, v172, s[10:11]
	v_fma_f32 v4, v0, -v2, -v174
	v_fma_f32 v122, 0, v2, v4
	v_add_f32_e32 v123, v2, v4
	v_pk_fma_f32 v[106:107], v[2:3], s[34:35], v[4:5] op_sel_hi:[0,1,0]
	v_pk_fma_f32 v[124:125], v[2:3], s[36:37], v[4:5] op_sel_hi:[0,1,0]
	v_pk_fma_f32 v[108:109], v[2:3], s[38:39], v[4:5] op_sel_hi:[0,1,0]
	v_pk_fma_f32 v[126:127], v[2:3], s[40:41], v[4:5] op_sel_hi:[0,1,0]
	v_pk_fma_f32 v[110:111], v[2:3], s[42:43], v[4:5] op_sel_hi:[0,1,0]
	v_pk_fma_f32 v[128:129], v[2:3], s[44:45], v[4:5] op_sel_hi:[0,1,0]
	v_pk_fma_f32 v[112:113], v[2:3], s[46:47], v[4:5] op_sel_hi:[0,1,0]
	v_pk_fma_f32 v[130:131], v[2:3], s[48:49], v[4:5] op_sel_hi:[0,1,0]
	v_pk_fma_f32 v[114:115], v[2:3], s[50:51], v[4:5] op_sel_hi:[0,1,0]
	v_pk_fma_f32 v[132:133], v[2:3], s[52:53], v[4:5] op_sel_hi:[0,1,0]
	v_pk_fma_f32 v[116:117], v[2:3], s[54:55], v[4:5] op_sel_hi:[0,1,0]
	v_pk_fma_f32 v[134:135], v[2:3], s[56:57], v[4:5] op_sel_hi:[0,1,0]
	v_pk_fma_f32 v[118:119], v[2:3], s[58:59], v[4:5] op_sel_hi:[0,1,0]
	v_fmamk_f32 v120, v2, 0x42680000, v4
	v_pk_fma_f32 v[136:137], v[2:3], s[60:61], v[4:5] op_sel_hi:[0,1,0]
	v_fmac_f32_e32 v4, 0x426c0000, v2
	s_mov_b64 s[4:5], 0
	v_mov_b32_e32 v121, v4

; #define SBAR() __builtin_amdgcn_sched_barrier(0)
; #define TILE_DQ(ti) (qposf - (float)TILE_KPOS(ti))
; #define TILE_SIDE(ti) (qlo - TILE_KPOS(ti) >= 63 ? 1 : (qhi - TILE_KPOS(ti) <= 0 ? -1 : 0))
; #define SWRITE(b, i) do { *(bf16x8*)((char*)V_lds + (b) * SHM_V + vst0) = sr_[i].vs0;          \
;     *(bf16x8*)((char*)V_lds + (b) * SHM_V + vst1) = sr_[i].vs1; int kc = sc * 2;               \
;     *(bf16x8*)((char*)K_lds + (b) * SHM_K + KSWZ(sr, kc)) = sr_[i].ks0;                       \
;     *(bf16x8*)((char*)K_lds + (b) * SHM_K + KSWZ(32 + sr, kc)) = sr_[i].ks1; } while (0)
; #define SWAIT() do { if constexpr (SDEPTH == 2) asm volatile("s_waitcnt vmcnt(4)" ::: "memory"); else asm volatile("s_waitcnt vmcnt(0)" ::: "memory"); } while (0)
; template <int J> ...
;     ...
;     __syncthreads(); SWAIT(); SWRITE(1, SO);
;     __syncthreads();
;   }
;   SBAR(); qkt<0>(pB0, pB1, (bf16*)((char*)K_lds + SHM_K), qr, r32, hi, TILE_DQ(NT - 1), nsl, TILE_SIDE(NT - 1), mi);
;   finishSM(pA0, pA1, l_reg, pa0, pa1, pa2, pa3); SBAR();
;   pv_d0(o, vb0, pa0, pa1, pa2, pa3); SBAR();
.Lmy_i2_exit0:
	s_waitcnt vmcnt(0)
	s_barrier
.Lmy_i2_exit:
	v_readfirstlane_b32 s92, v248
	s_add_i32 s4, s20, s14
	s_add_i32 s4, s4, -1
	s_ashr_i32 s5, s4, 31
	s_lshl_b64 s[4:5], s[4:5], 18
	s_add_u32 s4, s0, s4
	s_addc_u32 s5, s25, s5
	s_cmp_gt_i32 s14, s15
	s_cselect_b32 s4, s28, s4
	s_cselect_b32 s5, s29, s5
	s_add_i32 m0, s92, 0x4000
	s_nop 0
	global_load_lds_dwordx4 v247, s[4:5]
	s_add_i32 m0, s92, 0x4380
	s_nop 0
	global_load_lds_dwordx4 v247, s[4:5] offset:128
	s_branch .LBB0_764
